# EpiResidB (w2 / w_o GEMM epilogues): second-half residual-base loads hoisted above the first half's stores, on top of v43
# baseline (speedup 1.0000x reference)
; #define PG8_STAGE(bufoff, gbase, voff) do { _Pragma("unroll") for (int _i = 0; _i < 2; ++_i) \
;         __builtin_amdgcn_global_load_lds((const unsigned*)((const char*)(gbase) + (voff)[_i]), (LAS unsigned*)(lds + (bufoff) + ldsw + _i * 8192), 16, 0, 0); } while (0)
; #define PG8_LDA(dst, b, h) do { _Pragma("unroll") for (int m = 0; m < 4; ++m) _Pragma("unroll") for (int k = 0; k < 2; ++k) dst[m][k] = *(const LAS bf16x8*)(lds + PG8_SA(b, h) + aoff + m * 2048 + k * 1024); } while (0)
; #define PG8_LDB(dst, b, h) do { _Pragma("unroll") for (int n = 0; n < 2; ++n) _Pragma("unroll") for (int k = 0; k < 2; ++k) dst[n][k] = *(const LAS bf16x8*)(lds + PG8_SB(b, h) + boff + n * 2048 + k * 1024); } while (0)
; #define PG8_MMA(ai, bj, At, Bt) do { __builtin_amdgcn_s_setprio(1); _Pragma("unroll") for (int m = 0; m < 4; ++m) _Pragma("unroll") for (int n = 0; n < 2; ++n) _Pragma("unroll") for (int k = 0; k < 2; ++k) \
;         acc[ai][bj][m][n] = __builtin_amdgcn_mfma_f32_16x16x32_bf16(Bt[n][k], At[m][k], acc[ai][bj][m][n], 0, 0, 0); __builtin_amdgcn_s_setprio(0); } while (0)
; #define PG8_WAIT_L(n) asm volatile("s_waitcnt lgkmcnt(" #n ")" ::: "memory")
; #define PG8_BAR __builtin_amdgcn_s_barrier()
; #define PG8_SCHED __builtin_amdgcn_sched_barrier(0)
; template <class Epi>
; __device__ __forceinline__ void gemm_phase(LAS unsigned char* lds, const Gemm g, const Order& S, const Epi& E, const int tid) {
;     ...
;             PG8_LDB(B0, 0, 0); PG8_SCHED; PG8_LDA(At, 0, 0); PG8_STAGE(PG8_SA(1, 1), a1 + hstepA, voffA);
;             PG8_WAIT_L(8); PG8_BAR; PG8_WAIT_L(0); PG8_MMA(0, 0, At, B0); PG8_BAR; PG8_SCHED;
;             PG8_LDB(B1, 0, 1); PG8_STAGE(PG8_SB(0, 0), b2, voffB);
;             PG8_BAR; PG8_WAIT_L(0); PG8_MMA(0, 1, At, B1); PG8_BAR;
;             PG8_LDA(At, 0, 1); PG8_STAGE(PG8_SA(0, 0), a2, voffA);
;             PG8_BAR; PG8_WAIT_L(0); PG8_MMA(1, 0, At, B0); PG8_BAR; PG8_SCHED;
.LBB0_688:
	ds_read_b128 v[128:131], v189
	ds_read_b128 v[132:135], v189 offset:1024
	ds_read_b128 v[136:139], v189 offset:2048
	ds_read_b128 v[140:143], v189 offset:3072
	s_add_u32 s28, s26, 0xffe00080
	s_addc_u32 s29, s27, -1
	s_cmpk_eq_i32 s51, 0x7c
	s_cselect_b32 s31, s7, s29
	s_cselect_b32 s30, s15, s28
	s_cselect_b32 s29, s17, s50
	s_cselect_b32 s28, s48, s49
	v_lshl_add_u64 v[184:185], s[26:27], 0, v[160:161]
	s_add_i32 m0, s34, 0xc000
	ds_read_b128 v[144:147], v190
	ds_read_b128 v[148:151], v190 offset:1024
	ds_read_b128 v[168:171], v190 offset:2048
	ds_read_b128 v[172:175], v190 offset:3072
	ds_read_b128 v[176:179], v190 offset:4096
	ds_read_b128 v[180:183], v190 offset:5120
	ds_read_b128 v[194:197], v190 offset:6144
	ds_read_b128 v[198:201], v190 offset:7168
	global_load_lds_dwordx4 v[184:185], off
	v_lshl_add_u64 v[184:185], s[26:27], 0, v[162:163]
	s_add_i32 m0, s34, 0xe000
	s_nop 0
	global_load_lds_dwordx4 v[184:185], off
	s_waitcnt lgkmcnt(8)
	s_barrier
	s_waitcnt lgkmcnt(0)
	s_setprio 1
	s_waitcnt lgkmcnt(0)
	v_mfma_f32_16x16x32_bf16 v[124:127], v[128:131], v[144:147], v[124:127]
	v_mfma_f32_16x16x32_bf16 v[120:123], v[136:139], v[144:147], v[120:123]
	v_mfma_f32_16x16x32_bf16 v[108:111], v[128:131], v[168:171], v[108:111]
	v_mfma_f32_16x16x32_bf16 v[104:107], v[136:139], v[168:171], v[104:107]
	v_mfma_f32_16x16x32_bf16 v[92:95], v[128:131], v[176:179], v[92:95]
	v_mfma_f32_16x16x32_bf16 v[88:91], v[136:139], v[176:179], v[88:91]
	v_mfma_f32_16x16x32_bf16 v[76:79], v[128:131], v[194:197], v[76:79]
	v_mfma_f32_16x16x32_bf16 v[72:75], v[136:139], v[194:197], v[72:75]
	v_mfma_f32_16x16x32_bf16 v[124:127], v[132:135], v[148:151], v[124:127]
	v_mfma_f32_16x16x32_bf16 v[120:123], v[140:143], v[148:151], v[120:123]
	v_mfma_f32_16x16x32_bf16 v[108:111], v[132:135], v[172:175], v[108:111]
	v_mfma_f32_16x16x32_bf16 v[104:107], v[140:143], v[172:175], v[104:107]
	v_mfma_f32_16x16x32_bf16 v[92:95], v[132:135], v[180:183], v[92:95]
	v_mfma_f32_16x16x32_bf16 v[88:91], v[140:143], v[180:183], v[88:91]
	v_mfma_f32_16x16x32_bf16 v[76:79], v[132:135], v[198:201], v[76:79]
	v_mfma_f32_16x16x32_bf16 v[72:75], v[140:143], v[198:201], v[72:75]
	s_setprio 0
	s_barrier
	s_add_i32 s52, s45, s33
	v_lshl_add_u64 v[184:185], s[28:29], 0, v[154:155]
	s_mov_b32 m0, s52
	ds_read_b128 v[202:205], v191
	ds_read_b128 v[206:209], v191 offset:1024
	ds_read_b128 v[210:213], v191 offset:2048
	ds_read_b128 v[214:217], v191 offset:3072
	global_load_lds_dwordx4 v[184:185], off
	v_lshl_add_u64 v[218:219], s[28:29], 0, v[158:159]
	s_add_i32 m0, s52, 0x2000
	s_nop 0
	global_load_lds_dwordx4 v[218:219], off
	s_barrier
	s_waitcnt lgkmcnt(0)
	s_setprio 1
	s_waitcnt lgkmcnt(0)
	v_mfma_f32_16x16x32_bf16 v[116:119], v[202:205], v[144:147], v[116:119]
	v_mfma_f32_16x16x32_bf16 v[112:115], v[210:213], v[144:147], v[112:115]
	v_mfma_f32_16x16x32_bf16 v[100:103], v[202:205], v[168:171], v[100:103]
	v_mfma_f32_16x16x32_bf16 v[96:99], v[210:213], v[168:171], v[96:99]
	v_mfma_f32_16x16x32_bf16 v[84:87], v[202:205], v[176:179], v[84:87]
	v_mfma_f32_16x16x32_bf16 v[80:83], v[210:213], v[176:179], v[80:83]
	v_mfma_f32_16x16x32_bf16 v[68:71], v[202:205], v[194:197], v[68:71]
	v_mfma_f32_16x16x32_bf16 v[64:67], v[210:213], v[194:197], v[64:67]
	v_mfma_f32_16x16x32_bf16 v[116:119], v[206:209], v[148:151], v[116:119]
	v_mfma_f32_16x16x32_bf16 v[112:115], v[214:217], v[148:151], v[112:115]
	v_mfma_f32_16x16x32_bf16 v[100:103], v[206:209], v[172:175], v[100:103]
	v_mfma_f32_16x16x32_bf16 v[96:99], v[214:217], v[172:175], v[96:99]
	v_mfma_f32_16x16x32_bf16 v[84:87], v[206:209], v[180:183], v[84:87]
	v_mfma_f32_16x16x32_bf16 v[80:83], v[214:217], v[180:183], v[80:83]
	v_mfma_f32_16x16x32_bf16 v[68:71], v[206:209], v[198:201], v[68:71]
	v_mfma_f32_16x16x32_bf16 v[64:67], v[214:217], v[198:201], v[64:67]
	s_setprio 0
	s_mov_b32 m0, s34
	v_lshl_add_u64 v[220:221], s[30:31], 0, v[152:153]
	s_barrier
	ds_read_b128 v[144:147], v190 offset:16384
	ds_read_b128 v[148:151], v190 offset:17408
	ds_read_b128 v[168:171], v190 offset:18432
	ds_read_b128 v[172:175], v190 offset:19456
	ds_read_b128 v[176:179], v190 offset:20480
	ds_read_b128 v[180:183], v190 offset:21504
	ds_read_b128 v[194:197], v190 offset:22528
	ds_read_b128 v[198:201], v190 offset:23552
	global_load_lds_dwordx4 v[220:221], off
	v_lshl_add_u64 v[222:223], s[30:31], 0, v[156:157]
	s_mov_b32 m0, s35
	s_nop 0
	global_load_lds_dwordx4 v[222:223], off
	s_barrier
	s_waitcnt lgkmcnt(0)
	s_setprio 1
	s_waitcnt lgkmcnt(0)
	v_mfma_f32_16x16x32_bf16 v[60:63], v[128:131], v[144:147], v[60:63]
	v_mfma_f32_16x16x32_bf16 v[56:59], v[136:139], v[144:147], v[56:59]
	v_mfma_f32_16x16x32_bf16 v[44:47], v[128:131], v[168:171], v[44:47]
	v_mfma_f32_16x16x32_bf16 v[40:43], v[136:139], v[168:171], v[40:43]
	v_mfma_f32_16x16x32_bf16 v[28:31], v[128:131], v[176:179], v[28:31]
	v_mfma_f32_16x16x32_bf16 v[24:27], v[136:139], v[176:179], v[24:27]
	v_mfma_f32_16x16x32_bf16 v[12:15], v[128:131], v[194:197], v[12:15]
	v_mfma_f32_16x16x32_bf16 v[8:11], v[136:139], v[194:197], v[8:11]
	v_mfma_f32_16x16x32_bf16 v[60:63], v[132:135], v[148:151], v[60:63]
	v_mfma_f32_16x16x32_bf16 v[56:59], v[140:143], v[148:151], v[56:59]
	v_mfma_f32_16x16x32_bf16 v[44:47], v[132:135], v[172:175], v[44:47]
	v_mfma_f32_16x16x32_bf16 v[40:43], v[140:143], v[172:175], v[40:43]
	v_mfma_f32_16x16x32_bf16 v[28:31], v[132:135], v[180:183], v[28:31]
	v_mfma_f32_16x16x32_bf16 v[24:27], v[140:143], v[180:183], v[24:27]
	v_mfma_f32_16x16x32_bf16 v[12:15], v[132:135], v[198:201], v[12:15]
	v_mfma_f32_16x16x32_bf16 v[8:11], v[140:143], v[198:201], v[8:11]
	s_setprio 0
	s_barrier
; #define PG8_STAGE(bufoff, gbase, voff) do { _Pragma("unroll") for (int _i = 0; _i < 2; ++_i) \
;         __builtin_amdgcn_global_load_lds((const unsigned*)((const char*)(gbase) + (voff)[_i]), (LAS unsigned*)(lds + (bufoff) + ldsw + _i * 8192), 16, 0, 0); } while (0)
; #define PG8_LDA(dst, b, h) do { _Pragma("unroll") for (int m = 0; m < 4; ++m) _Pragma("unroll") for (int k = 0; k < 2; ++k) dst[m][k] = *(const LAS bf16x8*)(lds + PG8_SA(b, h) + aoff + m * 2048 + k * 1024); } while (0)
; #define PG8_LDB(dst, b, h) do { _Pragma("unroll") for (int n = 0; n < 2; ++n) _Pragma("unroll") for (int k = 0; k < 2; ++k) dst[n][k] = *(const LAS bf16x8*)(lds + PG8_SB(b, h) + boff + n * 2048 + k * 1024); } while (0)
; #define PG8_MMA(ai, bj, At, Bt) do { __builtin_amdgcn_s_setprio(1); _Pragma("unroll") for (int m = 0; m < 4; ++m) _Pragma("unroll") for (int n = 0; n < 2; ++n) _Pragma("unroll") for (int k = 0; k < 2; ++k) \
;         acc[ai][bj][m][n] = __builtin_amdgcn_mfma_f32_16x16x32_bf16(Bt[n][k], At[m][k], acc[ai][bj][m][n], 0, 0, 0); __builtin_amdgcn_s_setprio(0); } while (0)
; #define PG8_WAIT_V(n) asm volatile("s_waitcnt vmcnt(" #n ")" ::: "memory")
; #define PG8_WAIT_L(n) asm volatile("s_waitcnt lgkmcnt(" #n ")" ::: "memory")
; #define PG8_BAR __builtin_amdgcn_s_barrier()
; #define PG8_SCHED __builtin_amdgcn_sched_barrier(0)
; template <class Epi>
; __device__ __forceinline__ void gemm_phase(LAS unsigned char* lds, const Gemm g, const Order& S, const Epi& E, const int tid) {
;     ...
;             PG8_STAGE(PG8_SB(0, 1), b2 + hstepB, voffB);
;             PG8_WAIT_V(6); PG8_BAR; PG8_MMA(1, 1, At, B1); PG8_BAR;
;             PG8_LDB(B0, 1, 0); PG8_SCHED; PG8_LDA(At, 1, 0); PG8_STAGE(PG8_SA(0, 1), a2 + hstepA, voffA);
;             PG8_WAIT_L(8); PG8_BAR; PG8_WAIT_L(0); PG8_MMA(0, 0, At, B0); PG8_BAR; PG8_SCHED;
;             PG8_LDB(B1, 1, 1); PG8_STAGE(PG8_SB(1, 0), b3, voffB);
;             PG8_BAR; PG8_WAIT_L(0); PG8_MMA(0, 1, At, B1); PG8_BAR;
;             PG8_LDA(At, 1, 1); PG8_STAGE(PG8_SA(1, 0), a3, voffA);
	s_add_u32 s52, s28, 0x200000
	s_addc_u32 s53, s29, 0
	s_add_i32 s55, s46, s33
	v_lshl_add_u64 v[128:129], s[52:53], 0, v[154:155]
	s_mov_b32 m0, s55
	s_nop 0
	global_load_lds_dwordx4 v[128:129], off
	v_lshl_add_u64 v[128:129], s[52:53], 0, v[158:159]
	s_add_i32 m0, s55, 0x2000
	s_nop 0
	global_load_lds_dwordx4 v[128:129], off
	s_waitcnt vmcnt(6)
	s_barrier
	s_setprio 1
	v_mfma_f32_16x16x32_bf16 v[52:55], v[202:205], v[144:147], v[52:55]
	v_mfma_f32_16x16x32_bf16 v[48:51], v[210:213], v[144:147], v[48:51]
	v_mfma_f32_16x16x32_bf16 v[36:39], v[202:205], v[168:171], v[36:39]
	v_mfma_f32_16x16x32_bf16 v[32:35], v[210:213], v[168:171], v[32:35]
	v_mfma_f32_16x16x32_bf16 v[20:23], v[202:205], v[176:179], v[20:23]
	v_mfma_f32_16x16x32_bf16 v[16:19], v[210:213], v[176:179], v[16:19]
	v_mfma_f32_16x16x32_bf16 v[4:7], v[202:205], v[194:197], v[4:7]
	v_mfma_f32_16x16x32_bf16 v[0:3], v[210:213], v[194:197], v[0:3]
	v_mfma_f32_16x16x32_bf16 v[52:55], v[206:209], v[148:151], v[52:55]
	v_mfma_f32_16x16x32_bf16 v[48:51], v[214:217], v[148:151], v[48:51]
	v_mfma_f32_16x16x32_bf16 v[36:39], v[206:209], v[172:175], v[36:39]
	v_mfma_f32_16x16x32_bf16 v[32:35], v[214:217], v[172:175], v[32:35]
	v_mfma_f32_16x16x32_bf16 v[20:23], v[206:209], v[180:183], v[20:23]
	v_mfma_f32_16x16x32_bf16 v[16:19], v[214:217], v[180:183], v[16:19]
	v_mfma_f32_16x16x32_bf16 v[4:7], v[206:209], v[198:201], v[4:7]
	v_mfma_f32_16x16x32_bf16 v[0:3], v[214:217], v[198:201], v[0:3]
	s_setprio 0
	s_add_i32 s52, 0, 0x18000
	v_add_u32_e32 v140, s52, v187
	s_barrier
	ds_read_b128 v[128:131], v140
	ds_read_b128 v[132:135], v140 offset:1024
	ds_read_b128 v[136:139], v140 offset:2048
	ds_read_b128 v[140:143], v140 offset:3072
	s_add_u32 s30, s30, 0x200000
	s_addc_u32 s31, s31, 0
	s_mov_b32 m0, s39
	v_lshl_add_u64 v[202:203], s[30:31], 0, v[152:153]
	ds_read_b128 v[144:147], v190 offset:32768
	ds_read_b128 v[148:151], v190 offset:33792
	ds_read_b128 v[168:171], v190 offset:34816
	ds_read_b128 v[172:175], v190 offset:35840
	ds_read_b128 v[176:179], v190 offset:36864
	ds_read_b128 v[180:183], v190 offset:37888
	ds_read_b128 v[194:197], v190 offset:38912
	ds_read_b128 v[198:201], v190 offset:39936
	global_load_lds_dwordx4 v[202:203], off
	v_lshl_add_u64 v[202:203], s[30:31], 0, v[156:157]
	s_mov_b32 m0, s40
	s_nop 0
	global_load_lds_dwordx4 v[202:203], off
	s_waitcnt lgkmcnt(8)
	s_barrier
	s_waitcnt lgkmcnt(0)
	s_setprio 1
	s_waitcnt lgkmcnt(0)
	v_mfma_f32_16x16x32_bf16 v[124:127], v[128:131], v[144:147], v[124:127]
	v_mfma_f32_16x16x32_bf16 v[120:123], v[136:139], v[144:147], v[120:123]
	v_mfma_f32_16x16x32_bf16 v[108:111], v[128:131], v[168:171], v[108:111]
	v_mfma_f32_16x16x32_bf16 v[104:107], v[136:139], v[168:171], v[104:107]
	v_mfma_f32_16x16x32_bf16 v[92:95], v[128:131], v[176:179], v[92:95]
	v_mfma_f32_16x16x32_bf16 v[88:91], v[136:139], v[176:179], v[88:91]
	v_mfma_f32_16x16x32_bf16 v[76:79], v[128:131], v[194:197], v[76:79]
	v_mfma_f32_16x16x32_bf16 v[72:75], v[136:139], v[194:197], v[72:75]
	v_mfma_f32_16x16x32_bf16 v[124:127], v[132:135], v[148:151], v[124:127]
	v_mfma_f32_16x16x32_bf16 v[120:123], v[140:143], v[148:151], v[120:123]
	v_mfma_f32_16x16x32_bf16 v[108:111], v[132:135], v[172:175], v[108:111]
	v_mfma_f32_16x16x32_bf16 v[104:107], v[140:143], v[172:175], v[104:107]
	v_mfma_f32_16x16x32_bf16 v[92:95], v[132:135], v[180:183], v[92:95]
	v_mfma_f32_16x16x32_bf16 v[88:91], v[140:143], v[180:183], v[88:91]
	v_mfma_f32_16x16x32_bf16 v[76:79], v[132:135], v[198:201], v[76:79]
	v_mfma_f32_16x16x32_bf16 v[72:75], v[140:143], v[198:201], v[72:75]
	s_setprio 0
	s_barrier
	s_add_i32 s30, 0, 0x1c000
	s_add_i32 s31, s52, s33
	v_add_u32_e32 v193, s30, v187
	v_lshl_add_u64 v[184:185], v[184:185], 0, s[12:13]
	s_mov_b32 m0, s31
	ds_read_b128 v[202:205], v193
	ds_read_b128 v[206:209], v193 offset:1024
	ds_read_b128 v[210:213], v193 offset:2048
	ds_read_b128 v[214:217], v193 offset:3072
	global_load_lds_dwordx4 v[184:185], off
	v_lshl_add_u64 v[184:185], v[218:219], 0, s[12:13]
	s_add_i32 m0, s31, 0x2000
	s_nop 0
	global_load_lds_dwordx4 v[184:185], off
	s_barrier
	s_waitcnt lgkmcnt(0)
	s_setprio 1
	s_waitcnt lgkmcnt(0)
	v_mfma_f32_16x16x32_bf16 v[116:119], v[202:205], v[144:147], v[116:119]
	v_mfma_f32_16x16x32_bf16 v[112:115], v[210:213], v[144:147], v[112:115]
	v_mfma_f32_16x16x32_bf16 v[100:103], v[202:205], v[168:171], v[100:103]
	v_mfma_f32_16x16x32_bf16 v[96:99], v[210:213], v[168:171], v[96:99]
	v_mfma_f32_16x16x32_bf16 v[84:87], v[202:205], v[176:179], v[84:87]
	v_mfma_f32_16x16x32_bf16 v[80:83], v[210:213], v[176:179], v[80:83]
	v_mfma_f32_16x16x32_bf16 v[68:71], v[202:205], v[194:197], v[68:71]
	v_mfma_f32_16x16x32_bf16 v[64:67], v[210:213], v[194:197], v[64:67]
	v_mfma_f32_16x16x32_bf16 v[116:119], v[206:209], v[148:151], v[116:119]
	v_mfma_f32_16x16x32_bf16 v[112:115], v[214:217], v[148:151], v[112:115]
	v_mfma_f32_16x16x32_bf16 v[100:103], v[206:209], v[172:175], v[100:103]
	v_mfma_f32_16x16x32_bf16 v[96:99], v[214:217], v[172:175], v[96:99]
	v_mfma_f32_16x16x32_bf16 v[84:87], v[206:209], v[180:183], v[84:87]
	v_mfma_f32_16x16x32_bf16 v[80:83], v[214:217], v[180:183], v[80:83]
	v_mfma_f32_16x16x32_bf16 v[68:71], v[206:209], v[198:201], v[68:71]
	v_mfma_f32_16x16x32_bf16 v[64:67], v[214:217], v[198:201], v[64:67]
	s_setprio 0
	s_mov_b32 m0, s43
	v_lshl_add_u64 v[184:185], v[220:221], 0, s[12:13]
	s_barrier
	ds_read_b128 v[144:147], v190 offset:49152
	ds_read_b128 v[148:151], v190 offset:50176
	ds_read_b128 v[168:171], v190 offset:51200
	ds_read_b128 v[172:175], v190 offset:52224
	ds_read_b128 v[176:179], v190 offset:53248
	ds_read_b128 v[180:183], v190 offset:54272
	ds_read_b128 v[194:197], v190 offset:55296
	ds_read_b128 v[198:201], v190 offset:56320
	global_load_lds_dwordx4 v[184:185], off
	v_lshl_add_u64 v[184:185], v[222:223], 0, s[12:13]
	s_mov_b32 m0, s44
	s_nop 0
	global_load_lds_dwordx4 v[184:185], off
	s_barrier
; #define PG8_STAGE(bufoff, gbase, voff) do { _Pragma("unroll") for (int _i = 0; _i < 2; ++_i) \
;         __builtin_amdgcn_global_load_lds((const unsigned*)((const char*)(gbase) + (voff)[_i]), (LAS unsigned*)(lds + (bufoff) + ldsw + _i * 8192), 16, 0, 0); } while (0)
; #define PG8_MMA(ai, bj, At, Bt) do { __builtin_amdgcn_s_setprio(1); _Pragma("unroll") for (int m = 0; m < 4; ++m) _Pragma("unroll") for (int n = 0; n < 2; ++n) _Pragma("unroll") for (int k = 0; k < 2; ++k) \
;         acc[ai][bj][m][n] = __builtin_amdgcn_mfma_f32_16x16x32_bf16(Bt[n][k], At[m][k], acc[ai][bj][m][n], 0, 0, 0); __builtin_amdgcn_s_setprio(0); } while (0)
; #define PG8_WAIT_V(n) asm volatile("s_waitcnt vmcnt(" #n ")" ::: "memory")
; #define PG8_WAIT_L(n) asm volatile("s_waitcnt lgkmcnt(" #n ")" ::: "memory")
; #define PG8_BAR __builtin_amdgcn_s_barrier()
; #define PG8_SCHED __builtin_amdgcn_sched_barrier(0)
; template <class Epi>
; __device__ __forceinline__ void gemm_phase(LAS unsigned char* lds, const Gemm g, const Order& S, const Epi& E, const int tid) {
;     ...
;             PG8_BAR; PG8_WAIT_L(0); PG8_MMA(1, 0, At, B0); PG8_BAR; PG8_SCHED;
;             PG8_STAGE(PG8_SB(1, 1), b3 + hstepB, voffB);
;             PG8_WAIT_V(6); PG8_BAR; PG8_MMA(1, 1, At, B1); PG8_BAR;
	s_waitcnt lgkmcnt(0)
	s_setprio 1
	s_waitcnt lgkmcnt(0)
	v_mfma_f32_16x16x32_bf16 v[60:63], v[128:131], v[144:147], v[60:63]
	v_mfma_f32_16x16x32_bf16 v[56:59], v[136:139], v[144:147], v[56:59]
	v_mfma_f32_16x16x32_bf16 v[44:47], v[128:131], v[168:171], v[44:47]
	v_mfma_f32_16x16x32_bf16 v[40:43], v[136:139], v[168:171], v[40:43]
	v_mfma_f32_16x16x32_bf16 v[28:31], v[128:131], v[176:179], v[28:31]
	v_mfma_f32_16x16x32_bf16 v[24:27], v[136:139], v[176:179], v[24:27]
	v_mfma_f32_16x16x32_bf16 v[12:15], v[128:131], v[194:197], v[12:15]
	v_mfma_f32_16x16x32_bf16 v[8:11], v[136:139], v[194:197], v[8:11]
	v_mfma_f32_16x16x32_bf16 v[60:63], v[132:135], v[148:151], v[60:63]
	v_mfma_f32_16x16x32_bf16 v[56:59], v[140:143], v[148:151], v[56:59]
	v_mfma_f32_16x16x32_bf16 v[44:47], v[132:135], v[172:175], v[44:47]
	v_mfma_f32_16x16x32_bf16 v[40:43], v[140:143], v[172:175], v[40:43]
	v_mfma_f32_16x16x32_bf16 v[28:31], v[132:135], v[180:183], v[28:31]
	v_mfma_f32_16x16x32_bf16 v[24:27], v[140:143], v[180:183], v[24:27]
	v_mfma_f32_16x16x32_bf16 v[12:15], v[132:135], v[198:201], v[12:15]
	v_mfma_f32_16x16x32_bf16 v[8:11], v[140:143], v[198:201], v[8:11]
	s_setprio 0
	s_barrier
	s_add_u32 s28, s28, 0x200080
	s_addc_u32 s29, s29, 0
	s_add_i32 s30, s30, s33
	v_lshl_add_u64 v[128:129], s[28:29], 0, v[154:155]
	s_mov_b32 m0, s30
	s_nop 0
	global_load_lds_dwordx4 v[128:129], off
	v_lshl_add_u64 v[128:129], s[28:29], 0, v[158:159]
	s_add_i32 m0, s30, 0x2000
	s_nop 0
	global_load_lds_dwordx4 v[128:129], off
	s_waitcnt vmcnt(6)
	s_barrier
	s_setprio 1
	v_mfma_f32_16x16x32_bf16 v[52:55], v[202:205], v[144:147], v[52:55]
	v_mfma_f32_16x16x32_bf16 v[48:51], v[210:213], v[144:147], v[48:51]
	v_mfma_f32_16x16x32_bf16 v[36:39], v[202:205], v[168:171], v[36:39]
	v_mfma_f32_16x16x32_bf16 v[32:35], v[210:213], v[168:171], v[32:35]
	v_mfma_f32_16x16x32_bf16 v[20:23], v[202:205], v[176:179], v[20:23]
	v_mfma_f32_16x16x32_bf16 v[16:19], v[210:213], v[176:179], v[16:19]
	v_mfma_f32_16x16x32_bf16 v[4:7], v[202:205], v[194:197], v[4:7]
	v_mfma_f32_16x16x32_bf16 v[0:3], v[210:213], v[194:197], v[0:3]
	v_mfma_f32_16x16x32_bf16 v[52:55], v[206:209], v[148:151], v[52:55]
	v_mfma_f32_16x16x32_bf16 v[48:51], v[214:217], v[148:151], v[48:51]
	v_mfma_f32_16x16x32_bf16 v[36:39], v[206:209], v[172:175], v[36:39]
	v_mfma_f32_16x16x32_bf16 v[32:35], v[214:217], v[172:175], v[32:35]
	v_mfma_f32_16x16x32_bf16 v[20:23], v[206:209], v[180:183], v[20:23]
	v_mfma_f32_16x16x32_bf16 v[16:19], v[214:217], v[180:183], v[16:19]
	v_mfma_f32_16x16x32_bf16 v[4:7], v[206:209], v[198:201], v[4:7]
	v_mfma_f32_16x16x32_bf16 v[0:3], v[214:217], v[198:201], v[0:3]
	s_setprio 0
	s_add_i32 s51, s51, 2
	s_add_u32 s26, s26, 0x100
	s_addc_u32 s27, s27, 0
	s_add_u32 s49, s49, 0x100
	s_addc_u32 s50, s50, 0
	s_cmpk_gt_u32 s51, 0x7d
	s_barrier
	s_cbranch_scc0 .LBB0_688
; __device__ __forceinline__ float bflo(unsigned w) { return __uint_as_float(w << 16); }
; __device__ __forceinline__ float bfhi(unsigned w) { return __uint_as_float(w & 0xffff0000u); }
;     __device__ __forceinline__ void operator()(const f32x4 (&acc)[2][2][4][2], const Unit& u, int wr, int wc, int fr, int fq) const {
;     ...
;                 u32x4 bs[4][2];
; #pragma unroll
;                 for (int m = 0; m < 4; ++m) { const size_t off = (size_t)(row0 + ai * HALF + m * 16) * DM + col0;
; #pragma unroll
;                     for (int bj = 0; bj < 2; ++bj) bs[m][bj] = *(const u32x4*)(baseb + off + bj * HALF); }
; #pragma unroll
;                 for (int m = 0; m < 4; ++m) { const size_t off = (size_t)(row0 + ai * HALF + m * 16) * DM + col0;
;                     float ss = 0.f;
; #pragma unroll
;                     for (int bj = 0; bj < 2; ++bj) { const u32x4 q = bs[m][bj]; const f32x4 a0 = acc[ai][bj][m][0], a1 = acc[ai][bj][m][1];
;                         const float h0 = bflo(q.x) + a0[0], h1 = bfhi(q.x) + a0[1], h2 = bflo(q.y) + a0[2], h3 = bfhi(q.y) + a0[3], h4 = bflo(q.z) + a1[0], h5 = bfhi(q.z) + a1[1], h6 = bflo(q.w) + a1[2], h7 = bfhi(q.w) + a1[3];
;                         ss += (h0 * h0 + h1 * h1) + (h2 * h2 + h3 * h3) + (h4 * h4 + h5 * h5) + (h6 * h6 + h7 * h7);
;                         u32x4 w; w.x = pk2(h0, h1); w.y = pk2(h2, h3); w.z = pk2(h4, h5); w.w = pk2(h6, h7);
;                         *(u32x4*)(out + off + bj * HALF) = w; }
;                     if (ssqp) { ss += __shfl_xor(ss, 16); ss += __shfl_xor(ss, 32); if (fq == 0) ssqp[(size_t)(row0 + ai * HALF + m * 16) * 32 + u.pn * 4 + wc] = ss; } }
	v_lshl_or_b32 v168, s6, 8, v188
	v_lshl_add_u32 v172, s8, 8, v186
	v_ashrrev_i32_e32 v169, 31, v168
	v_lshlrev_b64 v[202:203], 1, v[168:169]
	v_ashrrev_i32_e32 v173, 31, v172
	v_or_b32_e32 v182, 16, v172
	v_or_b32_e32 v178, 32, v172
	v_lshl_add_u64 v[170:171], s[22:23], 0, v[202:203]
	v_lshlrev_b64 v[204:205], 12, v[172:173]
	v_or_b32_e32 v174, 48, v172
	v_ashrrev_i32_e32 v183, 31, v182
	v_ashrrev_i32_e32 v179, 31, v178
	v_lshl_add_u64 v[128:129], v[170:171], 0, v[204:205]
	v_ashrrev_i32_e32 v175, 31, v174
	v_lshlrev_b64 v[184:185], 12, v[182:183]
	v_lshlrev_b64 v[180:181], 12, v[178:179]
	global_load_dwordx4 v[194:197], v[128:129], off
	global_load_dwordx4 v[198:201], v[128:129], off offset:256
	v_lshlrev_b64 v[176:177], 12, v[174:175]
	v_lshl_add_u64 v[128:129], v[170:171], 0, v[184:185]
	v_lshl_add_u64 v[130:131], v[170:171], 0, v[180:181]
	v_lshl_add_u64 v[206:207], v[170:171], 0, v[176:177]
	global_load_dwordx4 v[148:151], v[128:129], off
	global_load_dwordx4 v[144:147], v[128:129], off offset:256
	global_load_dwordx4 v[140:143], v[130:131], off
	global_load_dwordx4 v[136:139], v[130:131], off offset:256
	global_load_dwordx4 v[132:135], v[206:207], off
	s_nop 0
	global_load_dwordx4 v[128:131], v[206:207], off offset:256
	s_mov_b64 s[100:101], 0x80000
	v_lshl_add_u64 v[244:245], v[170:171], 0, s[100:101]
	v_lshl_add_u64 v[246:247], v[244:245], 0, v[204:205]
	global_load_dwordx4 v[212:215], v[246:247], off
	global_load_dwordx4 v[216:219], v[246:247], off offset:256
	v_lshl_add_u64 v[246:247], v[244:245], 0, v[184:185]
	global_load_dwordx4 v[220:223], v[246:247], off
	global_load_dwordx4 v[224:227], v[246:247], off offset:256
	v_lshl_add_u64 v[246:247], v[244:245], 0, v[180:181]
	global_load_dwordx4 v[228:231], v[246:247], off
	global_load_dwordx4 v[232:235], v[246:247], off offset:256
	v_lshl_add_u64 v[246:247], v[244:245], 0, v[176:177]
	global_load_dwordx4 v[236:239], v[246:247], off
	global_load_dwordx4 v[240:243], v[246:247], off offset:256
	v_cndmask_b32_e64 v193, 0, 1, s[10:11]
	v_lshl_add_u64 v[204:205], s[22:23], 0, v[204:205]
	s_lshl_b32 s26, s6, 2
	v_cmp_ne_u32_e64 s[6:7], 1, v193
	v_lshl_add_u64 v[204:205], v[204:205], 0, v[202:203]
	s_ashr_i32 s27, s26, 31
	s_andn2_b64 vcc, exec, s[10:11]
	s_waitcnt vmcnt(0)
	v_lshlrev_b32_e32 v193, 16, v194
	v_and_b32_e32 v194, 0xffff0000, v194
	v_lshlrev_b32_e32 v202, 16, v195
	v_and_b32_e32 v195, 0xffff0000, v195
	v_lshlrev_b32_e32 v203, 16, v196
	v_and_b32_e32 v196, 0xffff0000, v196
	v_lshlrev_b32_e32 v206, 16, v197
	v_and_b32_e32 v197, 0xffff0000, v197
	v_lshlrev_b32_e32 v207, 16, v198
	v_and_b32_e32 v198, 0xffff0000, v198
	v_lshlrev_b32_e32 v208, 16, v199
	v_and_b32_e32 v199, 0xffff0000, v199
	v_lshlrev_b32_e32 v209, 16, v200
	v_and_b32_e32 v200, 0xffff0000, v200
	v_lshlrev_b32_e32 v210, 16, v201
	v_and_b32_e32 v201, 0xffff0000, v201
	v_add_f32_e32 v193, v124, v193
	v_add_f32_e32 v194, v125, v194
	v_add_f32_e32 v124, v126, v202
	v_add_f32_e32 v125, v127, v195
	v_add_f32_e32 v126, v120, v203
	v_add_f32_e32 v127, v121, v196
	v_add_f32_e32 v122, v122, v206
	v_add_f32_e32 v123, v123, v197
	v_add_f32_e32 v120, v116, v207
	v_add_f32_e32 v121, v117, v198
	v_add_f32_e32 v116, v118, v208
	v_add_f32_e32 v117, v119, v199
	v_add_f32_e32 v112, v112, v209
	v_add_f32_e32 v113, v113, v200
	v_add_f32_e32 v114, v114, v210
	v_add_f32_e32 v115, v115, v201
	v_cvt_pk_bf16_f32 v196, v193, v194
	v_cvt_pk_bf16_f32 v197, v124, v125
	v_cvt_pk_bf16_f32 v198, v126, v127
	v_cvt_pk_bf16_f32 v199, v122, v123
	v_cvt_pk_bf16_f32 v200, v120, v121
	v_cvt_pk_bf16_f32 v201, v116, v117
	v_cvt_pk_bf16_f32 v202, v112, v113
	v_cvt_pk_bf16_f32 v203, v114, v115
	global_store_dwordx4 v[204:205], v[196:199], off
	global_store_dwordx4 v[204:205], v[200:203], off offset:256
	s_cbranch_vccnz .LBB0_693
	v_mul_f32_e32 v115, v115, v115
	v_mul_f32_e32 v113, v113, v113
	v_mul_f32_e32 v118, v123, v123
	v_fmac_f32_e32 v115, v114, v114
	v_fmac_f32_e32 v113, v112, v112
	v_mul_f32_e32 v112, v121, v121
	v_mul_f32_e32 v114, v117, v117
	v_fmac_f32_e32 v118, v122, v122
	v_mul_f32_e32 v122, v194, v194
	v_mul_f32_e32 v123, v125, v125
	v_fmac_f32_e32 v112, v120, v120
	v_fmac_f32_e32 v114, v116, v116
	v_mul_f32_e32 v119, v127, v127
	v_fmac_f32_e32 v122, v193, v193
	v_fmac_f32_e32 v123, v124, v124
	v_add_f32_e32 v112, v112, v114
	v_and_b32_e32 v114, 64, v192
	v_fmac_f32_e32 v119, v126, v126
	v_add_f32_e32 v122, v122, v123
	v_add_f32_e32 v112, v113, v112
	v_xor_b32_e32 v113, 16, v192
	v_add_u32_e32 v114, 64, v114
	v_add_f32_e32 v119, v119, v122
	v_cmp_lt_i32_e32 vcc, v113, v114
	v_add_f32_e32 v118, v118, v119
	v_add_f32_e32 v112, v115, v112
	v_cndmask_b32_e32 v113, v192, v113, vcc
	v_add_f32_e32 v112, v118, v112
	v_lshlrev_b32_e32 v113, 2, v113
	ds_bpermute_b32 v113, v113, v112
	s_waitcnt lgkmcnt(0)
	v_add_f32_e32 v112, v112, v113
	v_xor_b32_e32 v113, 32, v192
	v_cmp_lt_i32_e32 vcc, v113, v114
	s_nop 1
	v_cndmask_b32_e32 v113, v192, v113, vcc
	v_lshlrev_b32_e32 v113, 2, v113
	ds_bpermute_b32 v113, v113, v112
	s_and_saveexec_b64 s[28:29], s[0:1]
	s_cbranch_execz .LBB0_692
	v_lshlrev_b64 v[114:115], 7, v[172:173]
	v_lshl_add_u64 v[114:115], s[24:25], 0, v[114:115]
	v_lshl_add_u64 v[114:115], s[26:27], 2, v[114:115]
	s_lshl_b32 s8, s41, 2
	v_lshl_add_u64 v[114:115], v[114:115], 0, s[8:9]
	s_waitcnt lgkmcnt(0)
	v_add_f32_e32 v112, v112, v113
	global_store_dword v[114:115], v112, off

; __device__ __forceinline__ float bflo(unsigned w) { return __uint_as_float(w << 16); }
; __device__ __forceinline__ float bfhi(unsigned w) { return __uint_as_float(w & 0xffff0000u); }
;     __device__ __forceinline__ void operator()(const f32x4 (&acc)[2][2][4][2], const Unit& u, int wr, int wc, int fr, int fq) const {
;     ...
;                 for (int m = 0; m < 4; ++m) { const size_t off = (size_t)(row0 + ai * HALF + m * 16) * DM + col0;
;                     float ss = 0.f;
; #pragma unroll
;                     for (int bj = 0; bj < 2; ++bj) { const u32x4 q = bs[m][bj]; const f32x4 a0 = acc[ai][bj][m][0], a1 = acc[ai][bj][m][1];
;                         const float h0 = bflo(q.x) + a0[0], h1 = bfhi(q.x) + a0[1], h2 = bflo(q.y) + a0[2], h3 = bfhi(q.y) + a0[3], h4 = bflo(q.z) + a1[0], h5 = bfhi(q.z) + a1[1], h6 = bflo(q.w) + a1[2], h7 = bfhi(q.w) + a1[3];
;                         ss += (h0 * h0 + h1 * h1) + (h2 * h2 + h3 * h3) + (h4 * h4 + h5 * h5) + (h6 * h6 + h7 * h7);
;                         u32x4 w; w.x = pk2(h0, h1); w.y = pk2(h2, h3); w.z = pk2(h4, h5); w.w = pk2(h6, h7);
;                         *(u32x4*)(out + off + bj * HALF) = w; }
;                     if (ssqp) { ss += __shfl_xor(ss, 16); ss += __shfl_xor(ss, 32); if (fq == 0) ssqp[(size_t)(row0 + ai * HALF + m * 16) * 32 + u.pn * 4 + wc] = ss; } }
.LBB0_705:
	v_add_u32_e32 v100, 0x80, v172
	v_ashrrev_i32_e32 v101, 31, v100
	v_add_u32_e32 v96, 0x90, v172
	v_add_u32_e32 v92, 0xa0, v172
	v_lshlrev_b64 v[110:111], 12, v[100:101]
	v_add_u32_e32 v88, 0xb0, v172
	s_waitcnt lgkmcnt(0)
	v_ashrrev_i32_e32 v97, 31, v96
	v_ashrrev_i32_e32 v93, 31, v92
	v_lshl_add_u64 v[64:65], v[170:171], 0, v[110:111]
	v_ashrrev_i32_e32 v89, 31, v88
	v_lshlrev_b64 v[98:99], 12, v[96:97]
	v_lshlrev_b64 v[94:95], 12, v[92:93]
	v_mov_b32_e32 v102, v212
	v_mov_b32_e32 v103, v213
	v_mov_b32_e32 v104, v214
	v_mov_b32_e32 v105, v215
	v_mov_b32_e32 v106, v216
	v_mov_b32_e32 v107, v217
	v_mov_b32_e32 v108, v218
	v_mov_b32_e32 v109, v219
	v_lshlrev_b64 v[90:91], 12, v[88:89]
	v_lshl_add_u64 v[64:65], v[170:171], 0, v[98:99]
	v_lshl_add_u64 v[66:67], v[170:171], 0, v[94:95]
	v_lshl_add_u64 v[112:113], v[170:171], 0, v[90:91]
	v_mov_b32_e32 v84, v220
	v_mov_b32_e32 v85, v221
	v_mov_b32_e32 v86, v222
	v_mov_b32_e32 v87, v223
	v_mov_b32_e32 v80, v224
	v_mov_b32_e32 v81, v225
	v_mov_b32_e32 v82, v226
	v_mov_b32_e32 v83, v227
	v_mov_b32_e32 v76, v228
	v_mov_b32_e32 v77, v229
	v_mov_b32_e32 v78, v230
	v_mov_b32_e32 v79, v231
	v_mov_b32_e32 v72, v232
	v_mov_b32_e32 v73, v233
	v_mov_b32_e32 v74, v234
	v_mov_b32_e32 v75, v235
	v_mov_b32_e32 v68, v236
	v_mov_b32_e32 v69, v237
	v_mov_b32_e32 v70, v238
	v_mov_b32_e32 v71, v239
	v_mov_b32_e32 v64, v240
	v_mov_b32_e32 v65, v241
	v_mov_b32_e32 v66, v242
	v_mov_b32_e32 v67, v243
	v_lshl_add_u64 v[110:111], s[22:23], 0, v[110:111]
	v_lshl_add_u64 v[112:113], v[168:169], 1, v[110:111]
	s_and_b64 vcc, exec, s[6:7]
	v_lshlrev_b32_e32 v110, 16, v102
	v_and_b32_e32 v111, 0xffff0000, v102
	v_lshlrev_b32_e32 v114, 16, v103
	v_and_b32_e32 v115, 0xffff0000, v103
	v_lshlrev_b32_e32 v116, 16, v104
	v_and_b32_e32 v104, 0xffff0000, v104
	v_lshlrev_b32_e32 v117, 16, v105
	v_and_b32_e32 v105, 0xffff0000, v105
	v_lshlrev_b32_e32 v118, 16, v106
	v_and_b32_e32 v106, 0xffff0000, v106
	v_lshlrev_b32_e32 v119, 16, v107
	v_and_b32_e32 v107, 0xffff0000, v107
	v_lshlrev_b32_e32 v120, 16, v108
	v_and_b32_e32 v108, 0xffff0000, v108
	v_lshlrev_b32_e32 v121, 16, v109
	v_and_b32_e32 v109, 0xffff0000, v109
	v_add_f32_e32 v102, v60, v110
	v_add_f32_e32 v103, v61, v111
	v_add_f32_e32 v60, v62, v114
	v_add_f32_e32 v61, v63, v115
	v_add_f32_e32 v62, v56, v116
	v_add_f32_e32 v63, v57, v104
	v_add_f32_e32 v58, v58, v117
	v_add_f32_e32 v59, v59, v105
	v_add_f32_e32 v56, v52, v118
	v_add_f32_e32 v57, v53, v106
	v_add_f32_e32 v52, v54, v119
	v_add_f32_e32 v53, v55, v107
	v_add_f32_e32 v48, v48, v120
	v_add_f32_e32 v49, v49, v108
	v_add_f32_e32 v50, v50, v121
	v_add_f32_e32 v51, v51, v109
	v_cvt_pk_bf16_f32 v104, v102, v103
	v_cvt_pk_bf16_f32 v105, v60, v61
	v_cvt_pk_bf16_f32 v106, v62, v63
	v_cvt_pk_bf16_f32 v107, v58, v59
	v_cvt_pk_bf16_f32 v108, v56, v57
	v_cvt_pk_bf16_f32 v109, v52, v53
	v_cvt_pk_bf16_f32 v110, v48, v49
	v_cvt_pk_bf16_f32 v111, v50, v51
	global_store_dwordx4 v[112:113], v[104:107], off
	global_store_dwordx4 v[112:113], v[108:111], off offset:256
	s_cbranch_vccnz .LBB0_709
	v_mul_f32_e32 v51, v51, v51
	v_mul_f32_e32 v49, v49, v49
	v_mul_f32_e32 v54, v59, v59
	v_fmac_f32_e32 v51, v50, v50
	v_fmac_f32_e32 v49, v48, v48
	v_mul_f32_e32 v48, v57, v57
	v_mul_f32_e32 v50, v53, v53
	v_fmac_f32_e32 v54, v58, v58
	v_mul_f32_e32 v58, v103, v103
	v_mul_f32_e32 v59, v61, v61
	v_fmac_f32_e32 v48, v56, v56
	v_fmac_f32_e32 v50, v52, v52
	v_mul_f32_e32 v55, v63, v63
	v_fmac_f32_e32 v58, v102, v102
	v_fmac_f32_e32 v59, v60, v60
	v_add_f32_e32 v48, v48, v50
	v_and_b32_e32 v50, 64, v192
	v_fmac_f32_e32 v55, v62, v62
	v_add_f32_e32 v58, v58, v59
	v_add_f32_e32 v48, v49, v48
	v_xor_b32_e32 v49, 16, v192
	v_add_u32_e32 v50, 64, v50
	v_add_f32_e32 v55, v55, v58
	v_cmp_lt_i32_e32 vcc, v49, v50
	v_add_f32_e32 v54, v54, v55
	v_add_f32_e32 v48, v51, v48
	v_cndmask_b32_e32 v49, v192, v49, vcc
	v_add_f32_e32 v48, v54, v48
	v_lshlrev_b32_e32 v49, 2, v49
	ds_bpermute_b32 v49, v49, v48
	s_waitcnt lgkmcnt(0)
	v_add_f32_e32 v48, v48, v49
	v_xor_b32_e32 v49, 32, v192
	v_cmp_lt_i32_e32 vcc, v49, v50
	s_nop 1
	v_cndmask_b32_e32 v49, v192, v49, vcc
	v_lshlrev_b32_e32 v49, 2, v49
	ds_bpermute_b32 v49, v49, v48
	s_and_saveexec_b64 s[28:29], s[0:1]
	s_cbranch_execz .LBB0_708
	v_lshlrev_b64 v[50:51], 7, v[100:101]
	v_lshl_add_u64 v[50:51], s[24:25], 0, v[50:51]
	v_lshl_add_u64 v[50:51], s[26:27], 2, v[50:51]
	s_lshl_b32 s8, s41, 2
	v_lshl_add_u64 v[50:51], v[50:51], 0, s[8:9]
	s_waitcnt lgkmcnt(0)
	v_add_f32_e32 v48, v48, v49
	global_store_dword v[50:51], v48, off

; __device__ __forceinline__ float bflo(unsigned w) { return __uint_as_float(w << 16); }
; __device__ __forceinline__ float bfhi(unsigned w) { return __uint_as_float(w & 0xffff0000u); }
;     __device__ __forceinline__ void operator()(const f32x4 (&acc)[2][2][4][2], const Unit& u, int wr, int wc, int fr, int fq) const {
;     ...
;                 for (int m = 0; m < 4; ++m) { const size_t off = (size_t)(row0 + ai * HALF + m * 16) * DM + col0;
;                     float ss = 0.f;
; #pragma unroll
;                     for (int bj = 0; bj < 2; ++bj) { const u32x4 q = bs[m][bj]; const f32x4 a0 = acc[ai][bj][m][0], a1 = acc[ai][bj][m][1];
;                         const float h0 = bflo(q.x) + a0[0], h1 = bfhi(q.x) + a0[1], h2 = bflo(q.y) + a0[2], h3 = bfhi(q.y) + a0[3], h4 = bflo(q.z) + a1[0], h5 = bfhi(q.z) + a1[1], h6 = bflo(q.w) + a1[2], h7 = bfhi(q.w) + a1[3];
;                         ss += (h0 * h0 + h1 * h1) + (h2 * h2 + h3 * h3) + (h4 * h4 + h5 * h5) + (h6 * h6 + h7 * h7);
;                         u32x4 w; w.x = pk2(h0, h1); w.y = pk2(h2, h3); w.z = pk2(h4, h5); w.w = pk2(h6, h7);
;                         *(u32x4*)(out + off + bj * HALF) = w; }
;                     if (ssqp) { ss += __shfl_xor(ss, 16); ss += __shfl_xor(ss, 32); if (fq == 0) ssqp[(size_t)(row0 + ai * HALF + m * 16) * 32 + u.pn * 4 + wc] = ss; } }
.LBB0_709:
	v_lshlrev_b32_e32 v48, 16, v84
	v_add_f32_e32 v44, v44, v48
	v_and_b32_e32 v48, 0xffff0000, v84
	v_add_f32_e32 v48, v45, v48
	v_lshlrev_b32_e32 v45, 16, v85
	v_add_f32_e32 v45, v46, v45
	v_and_b32_e32 v46, 0xffff0000, v85
	v_add_f32_e32 v46, v47, v46
	v_lshlrev_b32_e32 v47, 16, v86
	v_add_f32_e32 v40, v40, v47
	v_and_b32_e32 v47, 0xffff0000, v86
	v_add_f32_e32 v41, v41, v47
	v_lshlrev_b32_e32 v47, 16, v87
	v_add_f32_e32 v47, v42, v47
	v_and_b32_e32 v42, 0xffff0000, v87
	v_add_f32_e32 v43, v43, v42
	v_lshlrev_b32_e32 v42, 16, v80
	v_add_f32_e32 v36, v36, v42
	v_and_b32_e32 v42, 0xffff0000, v80
	v_add_f32_e32 v42, v37, v42
	v_lshlrev_b32_e32 v37, 16, v81
	v_add_f32_e32 v37, v38, v37
	v_and_b32_e32 v38, 0xffff0000, v81
	v_add_f32_e32 v38, v39, v38
	v_lshlrev_b32_e32 v39, 16, v82
	v_add_f32_e32 v32, v32, v39
	v_and_b32_e32 v39, 0xffff0000, v82
	v_add_f32_e32 v33, v33, v39
	v_lshlrev_b32_e32 v39, 16, v83
	v_lshl_add_u64 v[54:55], s[22:23], 0, v[98:99]
	v_add_f32_e32 v34, v34, v39
	v_and_b32_e32 v39, 0xffff0000, v83
	v_cvt_pk_bf16_f32 v50, v44, v48
	v_cvt_pk_bf16_f32 v51, v45, v46
	v_cvt_pk_bf16_f32 v52, v40, v41
	v_cvt_pk_bf16_f32 v53, v47, v43
	v_lshl_add_u64 v[54:55], v[168:169], 1, v[54:55]
	v_add_f32_e32 v35, v35, v39
	global_store_dwordx4 v[54:55], v[50:53], off
	s_and_b64 vcc, exec, s[6:7]
	s_nop 0
	v_cvt_pk_bf16_f32 v50, v36, v42
	v_cvt_pk_bf16_f32 v51, v37, v38
	v_cvt_pk_bf16_f32 v52, v32, v33
	v_cvt_pk_bf16_f32 v53, v34, v35
	global_store_dwordx4 v[54:55], v[50:53], off offset:256
	s_cbranch_vccnz .LBB0_713
	v_mul_f32_e32 v35, v35, v35
	v_mul_f32_e32 v33, v33, v33
	v_mul_f32_e32 v41, v41, v41
	v_fmac_f32_e32 v35, v34, v34
	v_fmac_f32_e32 v33, v32, v32
	v_mul_f32_e32 v32, v42, v42
	v_mul_f32_e32 v34, v38, v38
	v_mul_f32_e32 v39, v43, v43
	v_fmac_f32_e32 v41, v40, v40
	v_mul_f32_e32 v40, v48, v48
	v_mul_f32_e32 v43, v46, v46
	v_fmac_f32_e32 v32, v36, v36
	v_fmac_f32_e32 v34, v37, v37
	v_fmac_f32_e32 v40, v44, v44
	v_fmac_f32_e32 v43, v45, v45
	v_add_f32_e32 v32, v32, v34
	v_and_b32_e32 v34, 64, v192
	v_add_f32_e32 v40, v40, v43
	v_add_f32_e32 v32, v33, v32
	v_xor_b32_e32 v33, 16, v192
	v_add_u32_e32 v34, 64, v34
	v_fmac_f32_e32 v39, v47, v47
	v_add_f32_e32 v40, v41, v40
	v_cmp_lt_i32_e32 vcc, v33, v34
	v_add_f32_e32 v39, v39, v40
	v_add_f32_e32 v32, v35, v32
	v_cndmask_b32_e32 v33, v192, v33, vcc
	v_add_f32_e32 v32, v39, v32
	v_lshlrev_b32_e32 v33, 2, v33
	ds_bpermute_b32 v33, v33, v32
	s_waitcnt lgkmcnt(0)
	v_add_f32_e32 v32, v32, v33
	v_xor_b32_e32 v33, 32, v192
	v_cmp_lt_i32_e32 vcc, v33, v34
	s_nop 1
	v_cndmask_b32_e32 v33, v192, v33, vcc
	v_lshlrev_b32_e32 v33, 2, v33
	ds_bpermute_b32 v33, v33, v32
	s_and_saveexec_b64 s[28:29], s[0:1]
	s_cbranch_execz .LBB0_712
	v_lshlrev_b64 v[34:35], 7, v[96:97]
	v_lshl_add_u64 v[34:35], s[24:25], 0, v[34:35]
	v_lshl_add_u64 v[34:35], s[26:27], 2, v[34:35]
	s_lshl_b32 s8, s41, 2
	v_lshl_add_u64 v[34:35], v[34:35], 0, s[8:9]
	s_waitcnt lgkmcnt(0)
	v_add_f32_e32 v32, v32, v33
	global_store_dword v[34:35], v32, off

; __device__ __forceinline__ float bflo(unsigned w) { return __uint_as_float(w << 16); }
; __device__ __forceinline__ float bfhi(unsigned w) { return __uint_as_float(w & 0xffff0000u); }
;     __device__ __forceinline__ void operator()(const f32x4 (&acc)[2][2][4][2], const Unit& u, int wr, int wc, int fr, int fq) const {
;     ...
;                 for (int m = 0; m < 4; ++m) { const size_t off = (size_t)(row0 + ai * HALF + m * 16) * DM + col0;
;                     float ss = 0.f;
; #pragma unroll
;                     for (int bj = 0; bj < 2; ++bj) { const u32x4 q = bs[m][bj]; const f32x4 a0 = acc[ai][bj][m][0], a1 = acc[ai][bj][m][1];
;                         const float h0 = bflo(q.x) + a0[0], h1 = bfhi(q.x) + a0[1], h2 = bflo(q.y) + a0[2], h3 = bfhi(q.y) + a0[3], h4 = bflo(q.z) + a1[0], h5 = bfhi(q.z) + a1[1], h6 = bflo(q.w) + a1[2], h7 = bfhi(q.w) + a1[3];
;                         ss += (h0 * h0 + h1 * h1) + (h2 * h2 + h3 * h3) + (h4 * h4 + h5 * h5) + (h6 * h6 + h7 * h7);
;                         u32x4 w; w.x = pk2(h0, h1); w.y = pk2(h2, h3); w.z = pk2(h4, h5); w.w = pk2(h6, h7);
;                         *(u32x4*)(out + off + bj * HALF) = w; }
;                     if (ssqp) { ss += __shfl_xor(ss, 16); ss += __shfl_xor(ss, 32); if (fq == 0) ssqp[(size_t)(row0 + ai * HALF + m * 16) * 32 + u.pn * 4 + wc] = ss; } }
.LBB0_713:
	v_lshlrev_b32_e32 v32, 16, v76
	v_add_f32_e32 v28, v28, v32
	v_and_b32_e32 v32, 0xffff0000, v76
	v_add_f32_e32 v32, v29, v32
	v_lshlrev_b32_e32 v29, 16, v77
	v_add_f32_e32 v29, v30, v29
	v_and_b32_e32 v30, 0xffff0000, v77
	v_add_f32_e32 v30, v31, v30
	v_lshlrev_b32_e32 v31, 16, v78
	v_add_f32_e32 v24, v24, v31
	v_and_b32_e32 v31, 0xffff0000, v78
	v_add_f32_e32 v25, v25, v31
	v_lshlrev_b32_e32 v31, 16, v79
	v_add_f32_e32 v31, v26, v31
	v_and_b32_e32 v26, 0xffff0000, v79
	v_add_f32_e32 v27, v27, v26
	v_lshlrev_b32_e32 v26, 16, v72
	v_add_f32_e32 v20, v20, v26
	v_and_b32_e32 v26, 0xffff0000, v72
	v_add_f32_e32 v26, v21, v26
	v_lshlrev_b32_e32 v21, 16, v73
	v_add_f32_e32 v21, v22, v21
	v_and_b32_e32 v22, 0xffff0000, v73
	v_add_f32_e32 v22, v23, v22
	v_lshlrev_b32_e32 v23, 16, v74
	v_add_f32_e32 v16, v16, v23
	v_and_b32_e32 v23, 0xffff0000, v74
	v_add_f32_e32 v17, v17, v23
	v_lshlrev_b32_e32 v23, 16, v75
	v_lshl_add_u64 v[38:39], s[22:23], 0, v[94:95]
	v_add_f32_e32 v18, v18, v23
	v_and_b32_e32 v23, 0xffff0000, v75
	v_cvt_pk_bf16_f32 v34, v28, v32
	v_cvt_pk_bf16_f32 v35, v29, v30
	v_cvt_pk_bf16_f32 v36, v24, v25
	v_cvt_pk_bf16_f32 v37, v31, v27
	v_lshl_add_u64 v[38:39], v[168:169], 1, v[38:39]
	v_add_f32_e32 v19, v19, v23
	global_store_dwordx4 v[38:39], v[34:37], off
	s_and_b64 vcc, exec, s[6:7]
	s_nop 0
	v_cvt_pk_bf16_f32 v34, v20, v26
	v_cvt_pk_bf16_f32 v35, v21, v22
	v_cvt_pk_bf16_f32 v36, v16, v17
	v_cvt_pk_bf16_f32 v37, v18, v19
	global_store_dwordx4 v[38:39], v[34:37], off offset:256
	s_cbranch_vccnz .LBB0_717
	v_mul_f32_e32 v19, v19, v19
	v_mul_f32_e32 v17, v17, v17
	v_mul_f32_e32 v25, v25, v25
	v_fmac_f32_e32 v19, v18, v18
	v_fmac_f32_e32 v17, v16, v16
	v_mul_f32_e32 v16, v26, v26
	v_mul_f32_e32 v18, v22, v22
	v_mul_f32_e32 v23, v27, v27
	v_fmac_f32_e32 v25, v24, v24
	v_mul_f32_e32 v24, v32, v32
	v_mul_f32_e32 v27, v30, v30
	v_fmac_f32_e32 v16, v20, v20
	v_fmac_f32_e32 v18, v21, v21
	v_fmac_f32_e32 v24, v28, v28
	v_fmac_f32_e32 v27, v29, v29
	v_add_f32_e32 v16, v16, v18
	v_and_b32_e32 v18, 64, v192
	v_add_f32_e32 v24, v24, v27
	v_add_f32_e32 v16, v17, v16
	v_xor_b32_e32 v17, 16, v192
	v_add_u32_e32 v18, 64, v18
	v_fmac_f32_e32 v23, v31, v31
	v_add_f32_e32 v24, v25, v24
	v_cmp_lt_i32_e32 vcc, v17, v18
	v_add_f32_e32 v23, v23, v24
	v_add_f32_e32 v16, v19, v16
	v_cndmask_b32_e32 v17, v192, v17, vcc
	v_add_f32_e32 v16, v23, v16
	v_lshlrev_b32_e32 v17, 2, v17
	ds_bpermute_b32 v17, v17, v16
	s_waitcnt lgkmcnt(0)
	v_add_f32_e32 v16, v16, v17
	v_xor_b32_e32 v17, 32, v192
	v_cmp_lt_i32_e32 vcc, v17, v18
	s_nop 1
	v_cndmask_b32_e32 v17, v192, v17, vcc
	v_lshlrev_b32_e32 v17, 2, v17
	ds_bpermute_b32 v17, v17, v16
	s_and_saveexec_b64 s[28:29], s[0:1]
	s_cbranch_execz .LBB0_716
	v_lshlrev_b64 v[18:19], 7, v[92:93]
	v_lshl_add_u64 v[18:19], s[24:25], 0, v[18:19]
	v_lshl_add_u64 v[18:19], s[26:27], 2, v[18:19]
	s_lshl_b32 s8, s41, 2
	v_lshl_add_u64 v[18:19], v[18:19], 0, s[8:9]
	s_waitcnt lgkmcnt(0)
	v_add_f32_e32 v16, v16, v17
	global_store_dword v[18:19], v16, off

; __device__ __forceinline__ float bflo(unsigned w) { return __uint_as_float(w << 16); }
; __device__ __forceinline__ float bfhi(unsigned w) { return __uint_as_float(w & 0xffff0000u); }
;     __device__ __forceinline__ void operator()(const f32x4 (&acc)[2][2][4][2], const Unit& u, int wr, int wc, int fr, int fq) const {
;     ...
;                 for (int m = 0; m < 4; ++m) { const size_t off = (size_t)(row0 + ai * HALF + m * 16) * DM + col0;
;                     float ss = 0.f;
; #pragma unroll
;                     for (int bj = 0; bj < 2; ++bj) { const u32x4 q = bs[m][bj]; const f32x4 a0 = acc[ai][bj][m][0], a1 = acc[ai][bj][m][1];
;                         const float h0 = bflo(q.x) + a0[0], h1 = bfhi(q.x) + a0[1], h2 = bflo(q.y) + a0[2], h3 = bfhi(q.y) + a0[3], h4 = bflo(q.z) + a1[0], h5 = bfhi(q.z) + a1[1], h6 = bflo(q.w) + a1[2], h7 = bfhi(q.w) + a1[3];
;                         ss += (h0 * h0 + h1 * h1) + (h2 * h2 + h3 * h3) + (h4 * h4 + h5 * h5) + (h6 * h6 + h7 * h7);
;                         u32x4 w; w.x = pk2(h0, h1); w.y = pk2(h2, h3); w.z = pk2(h4, h5); w.w = pk2(h6, h7);
;                         *(u32x4*)(out + off + bj * HALF) = w; }
;                     if (ssqp) { ss += __shfl_xor(ss, 16); ss += __shfl_xor(ss, 32); if (fq == 0) ssqp[(size_t)(row0 + ai * HALF + m * 16) * 32 + u.pn * 4 + wc] = ss; } }
.LBB0_717:
	v_lshlrev_b32_e32 v16, 16, v68
	v_add_f32_e32 v12, v12, v16
	v_and_b32_e32 v16, 0xffff0000, v68
	v_add_f32_e32 v16, v13, v16
	v_lshlrev_b32_e32 v13, 16, v69
	v_add_f32_e32 v13, v14, v13
	v_and_b32_e32 v14, 0xffff0000, v69
	v_add_f32_e32 v14, v15, v14
	v_lshlrev_b32_e32 v15, 16, v70
	v_add_f32_e32 v8, v8, v15
	v_and_b32_e32 v15, 0xffff0000, v70
	v_add_f32_e32 v9, v9, v15
	v_lshlrev_b32_e32 v15, 16, v71
	v_add_f32_e32 v15, v10, v15
	v_and_b32_e32 v10, 0xffff0000, v71
	v_add_f32_e32 v11, v11, v10
	v_lshlrev_b32_e32 v10, 16, v64
	v_add_f32_e32 v4, v4, v10
	v_and_b32_e32 v10, 0xffff0000, v64
	v_add_f32_e32 v10, v5, v10
	v_lshlrev_b32_e32 v5, 16, v65
	v_add_f32_e32 v5, v6, v5
	v_and_b32_e32 v6, 0xffff0000, v65
	v_add_f32_e32 v6, v7, v6
	v_lshlrev_b32_e32 v7, 16, v66
	v_add_f32_e32 v0, v0, v7
	v_and_b32_e32 v7, 0xffff0000, v66
	v_add_f32_e32 v1, v1, v7
	v_lshlrev_b32_e32 v7, 16, v67
	v_lshl_add_u64 v[22:23], s[22:23], 0, v[90:91]
	v_add_f32_e32 v2, v2, v7
	v_and_b32_e32 v7, 0xffff0000, v67
	v_cvt_pk_bf16_f32 v18, v12, v16
	v_cvt_pk_bf16_f32 v19, v13, v14
	v_cvt_pk_bf16_f32 v20, v8, v9
	v_cvt_pk_bf16_f32 v21, v15, v11
	v_lshl_add_u64 v[22:23], v[168:169], 1, v[22:23]
	v_add_f32_e32 v3, v3, v7
	global_store_dwordx4 v[22:23], v[18:21], off
	s_and_b64 vcc, exec, s[6:7]
	s_nop 0
	v_cvt_pk_bf16_f32 v18, v4, v10
	v_cvt_pk_bf16_f32 v19, v5, v6
	v_cvt_pk_bf16_f32 v20, v0, v1
	v_cvt_pk_bf16_f32 v21, v2, v3
	global_store_dwordx4 v[22:23], v[18:21], off offset:256
	s_cbranch_vccnz .LBB0_680
	v_mul_f32_e32 v3, v3, v3
	v_mul_f32_e32 v1, v1, v1
	v_mul_f32_e32 v9, v9, v9
	v_fmac_f32_e32 v3, v2, v2
	v_fmac_f32_e32 v1, v0, v0
	v_mul_f32_e32 v0, v10, v10
	v_mul_f32_e32 v2, v6, v6
	v_mul_f32_e32 v7, v11, v11
	v_fmac_f32_e32 v9, v8, v8
	v_mul_f32_e32 v8, v16, v16
	v_mul_f32_e32 v11, v14, v14
	v_fmac_f32_e32 v0, v4, v4
	v_fmac_f32_e32 v2, v5, v5
	v_fmac_f32_e32 v8, v12, v12
	v_fmac_f32_e32 v11, v13, v13
	v_add_f32_e32 v0, v0, v2
	v_and_b32_e32 v2, 64, v192
	v_add_f32_e32 v8, v8, v11
	v_add_f32_e32 v0, v1, v0
	v_xor_b32_e32 v1, 16, v192
	v_add_u32_e32 v2, 64, v2
	v_fmac_f32_e32 v7, v15, v15
	v_add_f32_e32 v8, v9, v8
	v_cmp_lt_i32_e32 vcc, v1, v2
	v_add_f32_e32 v7, v7, v8
	v_add_f32_e32 v0, v3, v0
	v_cndmask_b32_e32 v1, v192, v1, vcc
	v_add_f32_e32 v0, v7, v0
	v_lshlrev_b32_e32 v1, 2, v1
	ds_bpermute_b32 v1, v1, v0
	s_waitcnt lgkmcnt(0)
	v_add_f32_e32 v0, v0, v1
	v_xor_b32_e32 v1, 32, v192
	v_cmp_lt_i32_e32 vcc, v1, v2
	s_nop 1
	v_cndmask_b32_e32 v1, v192, v1, vcc
	v_lshlrev_b32_e32 v1, 2, v1
	ds_bpermute_b32 v1, v1, v0
	s_and_saveexec_b64 s[6:7], s[0:1]
	s_cbranch_execz .LBB0_679
	v_lshlrev_b64 v[2:3], 7, v[88:89]
	v_lshl_add_u64 v[2:3], s[24:25], 0, v[2:3]
	v_lshl_add_u64 v[2:3], s[26:27], 2, v[2:3]
	s_lshl_b32 s8, s41, 2
	v_lshl_add_u64 v[2:3], v[2:3], 0, s[8:9]
	s_waitcnt lgkmcnt(0)
	v_add_f32_e32 v0, v0, v1
	global_store_dword v[2:3], v0, off
	s_branch .LBB0_679

; #define PG8_STAGE(bufoff, gbase, voff) do { _Pragma("unroll") for (int _i = 0; _i < 2; ++_i) \
;         __builtin_amdgcn_global_load_lds((const unsigned*)((const char*)(gbase) + (voff)[_i]), (LAS unsigned*)(lds + (bufoff) + ldsw + _i * 8192), 16, 0, 0); } while (0)
; #define PG8_LDA(dst, b, h) do { _Pragma("unroll") for (int m = 0; m < 4; ++m) _Pragma("unroll") for (int k = 0; k < 2; ++k) dst[m][k] = *(const LAS bf16x8*)(lds + PG8_SA(b, h) + aoff + m * 2048 + k * 1024); } while (0)
; #define PG8_LDB(dst, b, h) do { _Pragma("unroll") for (int n = 0; n < 2; ++n) _Pragma("unroll") for (int k = 0; k < 2; ++k) dst[n][k] = *(const LAS bf16x8*)(lds + PG8_SB(b, h) + boff + n * 2048 + k * 1024); } while (0)
; #define PG8_MMA(ai, bj, At, Bt) do { __builtin_amdgcn_s_setprio(1); _Pragma("unroll") for (int m = 0; m < 4; ++m) _Pragma("unroll") for (int n = 0; n < 2; ++n) _Pragma("unroll") for (int k = 0; k < 2; ++k) \
;         acc[ai][bj][m][n] = __builtin_amdgcn_mfma_f32_16x16x32_bf16(Bt[n][k], At[m][k], acc[ai][bj][m][n], 0, 0, 0); __builtin_amdgcn_s_setprio(0); } while (0)
; #define PG8_WAIT_V(n) asm volatile("s_waitcnt vmcnt(" #n ")" ::: "memory")
; #define PG8_WAIT_L(n) asm volatile("s_waitcnt lgkmcnt(" #n ")" ::: "memory")
; #define PG8_BAR __builtin_amdgcn_s_barrier()
; #define PG8_SCHED __builtin_amdgcn_sched_barrier(0)
; template <class Epi>
; __device__ __forceinline__ void gemm_phase(LAS unsigned char* lds, const Gemm g, const Order& S, const Epi& E, const int tid) {
;     ...
;             PG8_LDB(B0, 0, 0); PG8_SCHED; PG8_LDA(At, 0, 0); PG8_STAGE(PG8_SA(1, 1), a1 + hstepA, voffA);
;             PG8_WAIT_L(8); PG8_BAR; PG8_WAIT_L(0); PG8_MMA(0, 0, At, B0); PG8_BAR; PG8_SCHED;
;             PG8_LDB(B1, 0, 1); PG8_STAGE(PG8_SB(0, 0), b2, voffB);
;             PG8_BAR; PG8_WAIT_L(0); PG8_MMA(0, 1, At, B1); PG8_BAR;
;             PG8_LDA(At, 0, 1); PG8_STAGE(PG8_SA(0, 0), a2, voffA);
;             PG8_BAR; PG8_WAIT_L(0); PG8_MMA(1, 0, At, B0); PG8_BAR; PG8_SCHED;
;             PG8_STAGE(PG8_SB(0, 1), b2 + hstepB, voffB);
;             PG8_WAIT_V(6); PG8_BAR; PG8_MMA(1, 1, At, B1); PG8_BAR;
.LBB0_846:
	ds_read_b128 v[128:131], v189
	ds_read_b128 v[132:135], v189 offset:1024
	ds_read_b128 v[136:139], v189 offset:2048
	ds_read_b128 v[140:143], v189 offset:3072
	s_add_u32 s28, s26, 0xfff80080
	s_addc_u32 s29, s27, -1
	s_cmp_eq_u32 s50, 28
	s_cselect_b32 s31, s7, s29
	s_cselect_b32 s30, s15, s28
	s_cselect_b32 s29, s17, s49
	s_cselect_b32 s28, s47, s48
	v_lshl_add_u64 v[184:185], s[26:27], 0, v[160:161]
	s_add_i32 m0, s34, 0xc000
	ds_read_b128 v[144:147], v190
	ds_read_b128 v[148:151], v190 offset:1024
	ds_read_b128 v[168:171], v190 offset:2048
	ds_read_b128 v[172:175], v190 offset:3072
	ds_read_b128 v[176:179], v190 offset:4096
	ds_read_b128 v[180:183], v190 offset:5120
	ds_read_b128 v[194:197], v190 offset:6144
	ds_read_b128 v[198:201], v190 offset:7168
	global_load_lds_dwordx4 v[184:185], off
	v_lshl_add_u64 v[184:185], s[26:27], 0, v[162:163]
	s_add_i32 m0, s34, 0xe000
	s_nop 0
	global_load_lds_dwordx4 v[184:185], off
	s_waitcnt lgkmcnt(8)
	s_barrier
	s_waitcnt lgkmcnt(0)
	s_setprio 1
	s_waitcnt lgkmcnt(0)
	v_mfma_f32_16x16x32_bf16 v[124:127], v[128:131], v[144:147], v[124:127]
	v_mfma_f32_16x16x32_bf16 v[120:123], v[136:139], v[144:147], v[120:123]
	v_mfma_f32_16x16x32_bf16 v[108:111], v[128:131], v[168:171], v[108:111]
	v_mfma_f32_16x16x32_bf16 v[104:107], v[136:139], v[168:171], v[104:107]
	v_mfma_f32_16x16x32_bf16 v[92:95], v[128:131], v[176:179], v[92:95]
	v_mfma_f32_16x16x32_bf16 v[88:91], v[136:139], v[176:179], v[88:91]
	v_mfma_f32_16x16x32_bf16 v[76:79], v[128:131], v[194:197], v[76:79]
	v_mfma_f32_16x16x32_bf16 v[72:75], v[136:139], v[194:197], v[72:75]
	v_mfma_f32_16x16x32_bf16 v[124:127], v[132:135], v[148:151], v[124:127]
	v_mfma_f32_16x16x32_bf16 v[120:123], v[140:143], v[148:151], v[120:123]
	v_mfma_f32_16x16x32_bf16 v[108:111], v[132:135], v[172:175], v[108:111]
	v_mfma_f32_16x16x32_bf16 v[104:107], v[140:143], v[172:175], v[104:107]
	v_mfma_f32_16x16x32_bf16 v[92:95], v[132:135], v[180:183], v[92:95]
	v_mfma_f32_16x16x32_bf16 v[88:91], v[140:143], v[180:183], v[88:91]
	v_mfma_f32_16x16x32_bf16 v[76:79], v[132:135], v[198:201], v[76:79]
	v_mfma_f32_16x16x32_bf16 v[72:75], v[140:143], v[198:201], v[72:75]
	s_setprio 0
	s_barrier
	s_add_i32 s51, s44, s33
	v_lshl_add_u64 v[184:185], s[28:29], 0, v[154:155]
	s_mov_b32 m0, s51
	ds_read_b128 v[202:205], v191
	ds_read_b128 v[206:209], v191 offset:1024
	ds_read_b128 v[210:213], v191 offset:2048
	ds_read_b128 v[214:217], v191 offset:3072
	global_load_lds_dwordx4 v[184:185], off
	v_lshl_add_u64 v[218:219], s[28:29], 0, v[158:159]
	s_add_i32 m0, s51, 0x2000
	s_nop 0
	global_load_lds_dwordx4 v[218:219], off
	s_barrier
	s_waitcnt lgkmcnt(0)
	s_setprio 1
	s_waitcnt lgkmcnt(0)
	v_mfma_f32_16x16x32_bf16 v[116:119], v[202:205], v[144:147], v[116:119]
	v_mfma_f32_16x16x32_bf16 v[112:115], v[210:213], v[144:147], v[112:115]
	v_mfma_f32_16x16x32_bf16 v[100:103], v[202:205], v[168:171], v[100:103]
	v_mfma_f32_16x16x32_bf16 v[96:99], v[210:213], v[168:171], v[96:99]
	v_mfma_f32_16x16x32_bf16 v[84:87], v[202:205], v[176:179], v[84:87]
	v_mfma_f32_16x16x32_bf16 v[80:83], v[210:213], v[176:179], v[80:83]
	v_mfma_f32_16x16x32_bf16 v[68:71], v[202:205], v[194:197], v[68:71]
	v_mfma_f32_16x16x32_bf16 v[64:67], v[210:213], v[194:197], v[64:67]
	v_mfma_f32_16x16x32_bf16 v[116:119], v[206:209], v[148:151], v[116:119]
	v_mfma_f32_16x16x32_bf16 v[112:115], v[214:217], v[148:151], v[112:115]
	v_mfma_f32_16x16x32_bf16 v[100:103], v[206:209], v[172:175], v[100:103]
	v_mfma_f32_16x16x32_bf16 v[96:99], v[214:217], v[172:175], v[96:99]
	v_mfma_f32_16x16x32_bf16 v[84:87], v[206:209], v[180:183], v[84:87]
	v_mfma_f32_16x16x32_bf16 v[80:83], v[214:217], v[180:183], v[80:83]
	v_mfma_f32_16x16x32_bf16 v[68:71], v[206:209], v[198:201], v[68:71]
	v_mfma_f32_16x16x32_bf16 v[64:67], v[214:217], v[198:201], v[64:67]
	s_setprio 0
	s_mov_b32 m0, s34
	v_lshl_add_u64 v[220:221], s[30:31], 0, v[152:153]
	s_barrier
	ds_read_b128 v[144:147], v190 offset:16384
	ds_read_b128 v[148:151], v190 offset:17408
	ds_read_b128 v[168:171], v190 offset:18432
	ds_read_b128 v[172:175], v190 offset:19456
	ds_read_b128 v[176:179], v190 offset:20480
	ds_read_b128 v[180:183], v190 offset:21504
	ds_read_b128 v[194:197], v190 offset:22528
	ds_read_b128 v[198:201], v190 offset:23552
	global_load_lds_dwordx4 v[220:221], off
	v_lshl_add_u64 v[222:223], s[30:31], 0, v[156:157]
	s_mov_b32 m0, s35
	s_nop 0
	global_load_lds_dwordx4 v[222:223], off
	s_barrier
	s_waitcnt lgkmcnt(0)
	s_setprio 1
	s_waitcnt lgkmcnt(0)
	v_mfma_f32_16x16x32_bf16 v[60:63], v[128:131], v[144:147], v[60:63]
	v_mfma_f32_16x16x32_bf16 v[56:59], v[136:139], v[144:147], v[56:59]
	v_mfma_f32_16x16x32_bf16 v[44:47], v[128:131], v[168:171], v[44:47]
	v_mfma_f32_16x16x32_bf16 v[40:43], v[136:139], v[168:171], v[40:43]
	v_mfma_f32_16x16x32_bf16 v[28:31], v[128:131], v[176:179], v[28:31]
	v_mfma_f32_16x16x32_bf16 v[24:27], v[136:139], v[176:179], v[24:27]
	v_mfma_f32_16x16x32_bf16 v[12:15], v[128:131], v[194:197], v[12:15]
	v_mfma_f32_16x16x32_bf16 v[8:11], v[136:139], v[194:197], v[8:11]
	v_mfma_f32_16x16x32_bf16 v[60:63], v[132:135], v[148:151], v[60:63]
	v_mfma_f32_16x16x32_bf16 v[56:59], v[140:143], v[148:151], v[56:59]
	v_mfma_f32_16x16x32_bf16 v[44:47], v[132:135], v[172:175], v[44:47]
	v_mfma_f32_16x16x32_bf16 v[40:43], v[140:143], v[172:175], v[40:43]
	v_mfma_f32_16x16x32_bf16 v[28:31], v[132:135], v[180:183], v[28:31]
	v_mfma_f32_16x16x32_bf16 v[24:27], v[140:143], v[180:183], v[24:27]
	v_mfma_f32_16x16x32_bf16 v[12:15], v[132:135], v[198:201], v[12:15]
	v_mfma_f32_16x16x32_bf16 v[8:11], v[140:143], v[198:201], v[8:11]
	s_setprio 0
	s_barrier
; #define PG8_STAGE(bufoff, gbase, voff) do { _Pragma("unroll") for (int _i = 0; _i < 2; ++_i) \
;         __builtin_amdgcn_global_load_lds((const unsigned*)((const char*)(gbase) + (voff)[_i]), (LAS unsigned*)(lds + (bufoff) + ldsw + _i * 8192), 16, 0, 0); } while (0)
; #define PG8_LDA(dst, b, h) do { _Pragma("unroll") for (int m = 0; m < 4; ++m) _Pragma("unroll") for (int k = 0; k < 2; ++k) dst[m][k] = *(const LAS bf16x8*)(lds + PG8_SA(b, h) + aoff + m * 2048 + k * 1024); } while (0)
; #define PG8_LDB(dst, b, h) do { _Pragma("unroll") for (int n = 0; n < 2; ++n) _Pragma("unroll") for (int k = 0; k < 2; ++k) dst[n][k] = *(const LAS bf16x8*)(lds + PG8_SB(b, h) + boff + n * 2048 + k * 1024); } while (0)
; #define PG8_MMA(ai, bj, At, Bt) do { __builtin_amdgcn_s_setprio(1); _Pragma("unroll") for (int m = 0; m < 4; ++m) _Pragma("unroll") for (int n = 0; n < 2; ++n) _Pragma("unroll") for (int k = 0; k < 2; ++k) \
;         acc[ai][bj][m][n] = __builtin_amdgcn_mfma_f32_16x16x32_bf16(Bt[n][k], At[m][k], acc[ai][bj][m][n], 0, 0, 0); __builtin_amdgcn_s_setprio(0); } while (0)
; #define PG8_WAIT_V(n) asm volatile("s_waitcnt vmcnt(" #n ")" ::: "memory")
; #define PG8_WAIT_L(n) asm volatile("s_waitcnt lgkmcnt(" #n ")" ::: "memory")
; #define PG8_BAR __builtin_amdgcn_s_barrier()
; #define PG8_SCHED __builtin_amdgcn_sched_barrier(0)
; template <class Epi>
; __device__ __forceinline__ void gemm_phase(LAS unsigned char* lds, const Gemm g, const Order& S, const Epi& E, const int tid) {
;     ...
;             PG8_WAIT_V(6); PG8_BAR; PG8_MMA(1, 1, At, B1); PG8_BAR;
;             PG8_LDB(B0, 1, 0); PG8_SCHED; PG8_LDA(At, 1, 0); PG8_STAGE(PG8_SA(0, 1), a2 + hstepA, voffA);
;             PG8_WAIT_L(8); PG8_BAR; PG8_WAIT_L(0); PG8_MMA(0, 0, At, B0); PG8_BAR; PG8_SCHED;
;             PG8_LDB(B1, 1, 1); PG8_STAGE(PG8_SB(1, 0), b3, voffB);
;             PG8_BAR; PG8_WAIT_L(0); PG8_MMA(0, 1, At, B1); PG8_BAR;
;             PG8_LDA(At, 1, 1); PG8_STAGE(PG8_SA(1, 0), a3, voffA);
;             PG8_BAR; PG8_WAIT_L(0); PG8_MMA(1, 0, At, B0); PG8_BAR; PG8_SCHED;
	s_add_u32 s52, s28, 0x80000
	s_addc_u32 s53, s29, 0
	s_add_i32 s51, s45, s33
	v_lshl_add_u64 v[128:129], s[52:53], 0, v[154:155]
	s_mov_b32 m0, s51
	s_nop 0
	global_load_lds_dwordx4 v[128:129], off
	v_lshl_add_u64 v[128:129], s[52:53], 0, v[158:159]
	s_add_i32 m0, s51, 0x2000
	s_nop 0
	global_load_lds_dwordx4 v[128:129], off
	s_waitcnt vmcnt(6)
	s_barrier
	s_setprio 1
	v_mfma_f32_16x16x32_bf16 v[52:55], v[202:205], v[144:147], v[52:55]
	v_mfma_f32_16x16x32_bf16 v[48:51], v[210:213], v[144:147], v[48:51]
	v_mfma_f32_16x16x32_bf16 v[36:39], v[202:205], v[168:171], v[36:39]
	v_mfma_f32_16x16x32_bf16 v[32:35], v[210:213], v[168:171], v[32:35]
	v_mfma_f32_16x16x32_bf16 v[20:23], v[202:205], v[176:179], v[20:23]
	v_mfma_f32_16x16x32_bf16 v[16:19], v[210:213], v[176:179], v[16:19]
	v_mfma_f32_16x16x32_bf16 v[4:7], v[202:205], v[194:197], v[4:7]
	v_mfma_f32_16x16x32_bf16 v[0:3], v[210:213], v[194:197], v[0:3]
	v_mfma_f32_16x16x32_bf16 v[52:55], v[206:209], v[148:151], v[52:55]
	v_mfma_f32_16x16x32_bf16 v[48:51], v[214:217], v[148:151], v[48:51]
	v_mfma_f32_16x16x32_bf16 v[36:39], v[206:209], v[172:175], v[36:39]
	v_mfma_f32_16x16x32_bf16 v[32:35], v[214:217], v[172:175], v[32:35]
	v_mfma_f32_16x16x32_bf16 v[20:23], v[206:209], v[180:183], v[20:23]
	v_mfma_f32_16x16x32_bf16 v[16:19], v[214:217], v[180:183], v[16:19]
	v_mfma_f32_16x16x32_bf16 v[4:7], v[206:209], v[198:201], v[4:7]
	v_mfma_f32_16x16x32_bf16 v[0:3], v[214:217], v[198:201], v[0:3]
	s_setprio 0
	s_add_i32 s51, 0, 0x18000
	v_add_u32_e32 v140, s51, v187
	s_barrier
	ds_read_b128 v[128:131], v140
	ds_read_b128 v[132:135], v140 offset:1024
	ds_read_b128 v[136:139], v140 offset:2048
	ds_read_b128 v[140:143], v140 offset:3072
	s_add_u32 s30, s30, 0x80000
	s_addc_u32 s31, s31, 0
	s_mov_b32 m0, s38
	v_lshl_add_u64 v[202:203], s[30:31], 0, v[152:153]
	ds_read_b128 v[144:147], v190 offset:32768
	ds_read_b128 v[148:151], v190 offset:33792
	ds_read_b128 v[168:171], v190 offset:34816
	ds_read_b128 v[172:175], v190 offset:35840
	ds_read_b128 v[176:179], v190 offset:36864
	ds_read_b128 v[180:183], v190 offset:37888
	ds_read_b128 v[194:197], v190 offset:38912
	ds_read_b128 v[198:201], v190 offset:39936
	global_load_lds_dwordx4 v[202:203], off
	v_lshl_add_u64 v[202:203], s[30:31], 0, v[156:157]
	s_mov_b32 m0, s39
	s_nop 0
	global_load_lds_dwordx4 v[202:203], off
	s_waitcnt lgkmcnt(8)
	s_barrier
	s_waitcnt lgkmcnt(0)
	s_setprio 1
	s_waitcnt lgkmcnt(0)
	v_mfma_f32_16x16x32_bf16 v[124:127], v[128:131], v[144:147], v[124:127]
	v_mfma_f32_16x16x32_bf16 v[120:123], v[136:139], v[144:147], v[120:123]
	v_mfma_f32_16x16x32_bf16 v[108:111], v[128:131], v[168:171], v[108:111]
	v_mfma_f32_16x16x32_bf16 v[104:107], v[136:139], v[168:171], v[104:107]
	v_mfma_f32_16x16x32_bf16 v[92:95], v[128:131], v[176:179], v[92:95]
	v_mfma_f32_16x16x32_bf16 v[88:91], v[136:139], v[176:179], v[88:91]
	v_mfma_f32_16x16x32_bf16 v[76:79], v[128:131], v[194:197], v[76:79]
	v_mfma_f32_16x16x32_bf16 v[72:75], v[136:139], v[194:197], v[72:75]
	v_mfma_f32_16x16x32_bf16 v[124:127], v[132:135], v[148:151], v[124:127]
	v_mfma_f32_16x16x32_bf16 v[120:123], v[140:143], v[148:151], v[120:123]
	v_mfma_f32_16x16x32_bf16 v[108:111], v[132:135], v[172:175], v[108:111]
	v_mfma_f32_16x16x32_bf16 v[104:107], v[140:143], v[172:175], v[104:107]
	v_mfma_f32_16x16x32_bf16 v[92:95], v[132:135], v[180:183], v[92:95]
	v_mfma_f32_16x16x32_bf16 v[88:91], v[140:143], v[180:183], v[88:91]
	v_mfma_f32_16x16x32_bf16 v[76:79], v[132:135], v[198:201], v[76:79]
	v_mfma_f32_16x16x32_bf16 v[72:75], v[140:143], v[198:201], v[72:75]
	s_setprio 0
	s_barrier
	s_add_i32 s30, 0, 0x1c000
	s_add_i32 s31, s51, s33
	v_add_u32_e32 v193, s30, v187
	v_lshl_add_u64 v[184:185], v[184:185], 0, s[12:13]
	s_mov_b32 m0, s31
	ds_read_b128 v[202:205], v193
	ds_read_b128 v[206:209], v193 offset:1024
	ds_read_b128 v[210:213], v193 offset:2048
	ds_read_b128 v[214:217], v193 offset:3072
	global_load_lds_dwordx4 v[184:185], off
	v_lshl_add_u64 v[184:185], v[218:219], 0, s[12:13]
	s_add_i32 m0, s31, 0x2000
	s_nop 0
	global_load_lds_dwordx4 v[184:185], off
	s_barrier
	s_waitcnt lgkmcnt(0)
	s_setprio 1
	s_waitcnt lgkmcnt(0)
	v_mfma_f32_16x16x32_bf16 v[116:119], v[202:205], v[144:147], v[116:119]
	v_mfma_f32_16x16x32_bf16 v[112:115], v[210:213], v[144:147], v[112:115]
	v_mfma_f32_16x16x32_bf16 v[100:103], v[202:205], v[168:171], v[100:103]
	v_mfma_f32_16x16x32_bf16 v[96:99], v[210:213], v[168:171], v[96:99]
	v_mfma_f32_16x16x32_bf16 v[84:87], v[202:205], v[176:179], v[84:87]
	v_mfma_f32_16x16x32_bf16 v[80:83], v[210:213], v[176:179], v[80:83]
	v_mfma_f32_16x16x32_bf16 v[68:71], v[202:205], v[194:197], v[68:71]
	v_mfma_f32_16x16x32_bf16 v[64:67], v[210:213], v[194:197], v[64:67]
	v_mfma_f32_16x16x32_bf16 v[116:119], v[206:209], v[148:151], v[116:119]
	v_mfma_f32_16x16x32_bf16 v[112:115], v[214:217], v[148:151], v[112:115]
	v_mfma_f32_16x16x32_bf16 v[100:103], v[206:209], v[172:175], v[100:103]
	v_mfma_f32_16x16x32_bf16 v[96:99], v[214:217], v[172:175], v[96:99]
	v_mfma_f32_16x16x32_bf16 v[84:87], v[206:209], v[180:183], v[84:87]
	v_mfma_f32_16x16x32_bf16 v[80:83], v[214:217], v[180:183], v[80:83]
	v_mfma_f32_16x16x32_bf16 v[68:71], v[206:209], v[198:201], v[68:71]
	v_mfma_f32_16x16x32_bf16 v[64:67], v[214:217], v[198:201], v[64:67]
	s_setprio 0
	s_mov_b32 m0, s42
	v_lshl_add_u64 v[184:185], v[220:221], 0, s[12:13]
	s_barrier
	ds_read_b128 v[144:147], v190 offset:49152
	ds_read_b128 v[148:151], v190 offset:50176
	ds_read_b128 v[168:171], v190 offset:51200
	ds_read_b128 v[172:175], v190 offset:52224
	ds_read_b128 v[176:179], v190 offset:53248
	ds_read_b128 v[180:183], v190 offset:54272
	ds_read_b128 v[194:197], v190 offset:55296
	ds_read_b128 v[198:201], v190 offset:56320
	global_load_lds_dwordx4 v[184:185], off
	v_lshl_add_u64 v[184:185], v[222:223], 0, s[12:13]
	s_mov_b32 m0, s43
	s_nop 0
	global_load_lds_dwordx4 v[184:185], off
	s_barrier
; #define PG8_STAGE(bufoff, gbase, voff) do { _Pragma("unroll") for (int _i = 0; _i < 2; ++_i) \
;         __builtin_amdgcn_global_load_lds((const unsigned*)((const char*)(gbase) + (voff)[_i]), (LAS unsigned*)(lds + (bufoff) + ldsw + _i * 8192), 16, 0, 0); } while (0)
; #define PG8_MMA(ai, bj, At, Bt) do { __builtin_amdgcn_s_setprio(1); _Pragma("unroll") for (int m = 0; m < 4; ++m) _Pragma("unroll") for (int n = 0; n < 2; ++n) _Pragma("unroll") for (int k = 0; k < 2; ++k) \
;         acc[ai][bj][m][n] = __builtin_amdgcn_mfma_f32_16x16x32_bf16(Bt[n][k], At[m][k], acc[ai][bj][m][n], 0, 0, 0); __builtin_amdgcn_s_setprio(0); } while (0)
; #define PG8_WAIT_V(n) asm volatile("s_waitcnt vmcnt(" #n ")" ::: "memory")
; #define PG8_WAIT_L(n) asm volatile("s_waitcnt lgkmcnt(" #n ")" ::: "memory")
; #define PG8_BAR __builtin_amdgcn_s_barrier()
; #define PG8_SCHED __builtin_amdgcn_sched_barrier(0)
; template <class Epi>
; __device__ __forceinline__ void gemm_phase(LAS unsigned char* lds, const Gemm g, const Order& S, const Epi& E, const int tid) {
;     ...
;             PG8_BAR; PG8_WAIT_L(0); PG8_MMA(1, 0, At, B0); PG8_BAR; PG8_SCHED;
;             PG8_STAGE(PG8_SB(1, 1), b3 + hstepB, voffB);
;             PG8_WAIT_V(6); PG8_BAR; PG8_MMA(1, 1, At, B1); PG8_BAR;
;         }
	s_waitcnt lgkmcnt(0)
	s_setprio 1
	s_waitcnt lgkmcnt(0)
	v_mfma_f32_16x16x32_bf16 v[60:63], v[128:131], v[144:147], v[60:63]
	v_mfma_f32_16x16x32_bf16 v[56:59], v[136:139], v[144:147], v[56:59]
	v_mfma_f32_16x16x32_bf16 v[44:47], v[128:131], v[168:171], v[44:47]
	v_mfma_f32_16x16x32_bf16 v[40:43], v[136:139], v[168:171], v[40:43]
	v_mfma_f32_16x16x32_bf16 v[28:31], v[128:131], v[176:179], v[28:31]
	v_mfma_f32_16x16x32_bf16 v[24:27], v[136:139], v[176:179], v[24:27]
	v_mfma_f32_16x16x32_bf16 v[12:15], v[128:131], v[194:197], v[12:15]
	v_mfma_f32_16x16x32_bf16 v[8:11], v[136:139], v[194:197], v[8:11]
	v_mfma_f32_16x16x32_bf16 v[60:63], v[132:135], v[148:151], v[60:63]
	v_mfma_f32_16x16x32_bf16 v[56:59], v[140:143], v[148:151], v[56:59]
	v_mfma_f32_16x16x32_bf16 v[44:47], v[132:135], v[172:175], v[44:47]
	v_mfma_f32_16x16x32_bf16 v[40:43], v[140:143], v[172:175], v[40:43]
	v_mfma_f32_16x16x32_bf16 v[28:31], v[132:135], v[180:183], v[28:31]
	v_mfma_f32_16x16x32_bf16 v[24:27], v[140:143], v[180:183], v[24:27]
	v_mfma_f32_16x16x32_bf16 v[12:15], v[132:135], v[198:201], v[12:15]
	v_mfma_f32_16x16x32_bf16 v[8:11], v[140:143], v[198:201], v[8:11]
	s_setprio 0
	s_barrier
	s_add_u32 s28, s28, 0x80080
	s_addc_u32 s29, s29, 0
	s_add_i32 s30, s30, s33
	v_lshl_add_u64 v[128:129], s[28:29], 0, v[154:155]
	s_mov_b32 m0, s30
	s_nop 0
	global_load_lds_dwordx4 v[128:129], off
	v_lshl_add_u64 v[128:129], s[28:29], 0, v[158:159]
	s_add_i32 m0, s30, 0x2000
	s_nop 0
	global_load_lds_dwordx4 v[128:129], off
	s_waitcnt vmcnt(6)
	s_barrier
	s_setprio 1
	v_mfma_f32_16x16x32_bf16 v[52:55], v[202:205], v[144:147], v[52:55]
	v_mfma_f32_16x16x32_bf16 v[48:51], v[210:213], v[144:147], v[48:51]
	v_mfma_f32_16x16x32_bf16 v[36:39], v[202:205], v[168:171], v[36:39]
	v_mfma_f32_16x16x32_bf16 v[32:35], v[210:213], v[168:171], v[32:35]
	v_mfma_f32_16x16x32_bf16 v[20:23], v[202:205], v[176:179], v[20:23]
	v_mfma_f32_16x16x32_bf16 v[16:19], v[210:213], v[176:179], v[16:19]
	v_mfma_f32_16x16x32_bf16 v[4:7], v[202:205], v[194:197], v[4:7]
	v_mfma_f32_16x16x32_bf16 v[0:3], v[210:213], v[194:197], v[0:3]
	v_mfma_f32_16x16x32_bf16 v[52:55], v[206:209], v[148:151], v[52:55]
	v_mfma_f32_16x16x32_bf16 v[48:51], v[214:217], v[148:151], v[48:51]
	v_mfma_f32_16x16x32_bf16 v[36:39], v[206:209], v[172:175], v[36:39]
	v_mfma_f32_16x16x32_bf16 v[32:35], v[214:217], v[172:175], v[32:35]
	v_mfma_f32_16x16x32_bf16 v[20:23], v[206:209], v[180:183], v[20:23]
	v_mfma_f32_16x16x32_bf16 v[16:19], v[214:217], v[180:183], v[16:19]
	v_mfma_f32_16x16x32_bf16 v[4:7], v[206:209], v[198:201], v[4:7]
	v_mfma_f32_16x16x32_bf16 v[0:3], v[214:217], v[198:201], v[0:3]
	s_setprio 0
	s_add_i32 s50, s50, 2
	s_add_u32 s26, s26, 0x100
	s_addc_u32 s27, s27, 0
	s_add_u32 s48, s48, 0x100
	s_addc_u32 s49, s49, 0
	s_cmp_gt_u32 s50, 29
	s_barrier
	s_cbranch_scc0 .LBB0_846
; __device__ __forceinline__ float bflo(unsigned w) { return __uint_as_float(w << 16); }
; __device__ __forceinline__ float bfhi(unsigned w) { return __uint_as_float(w & 0xffff0000u); }
;     __device__ __forceinline__ void operator()(const f32x4 (&acc)[2][2][4][2], const Unit& u, int wr, int wc, int fr, int fq) const {
;     ...
;                 u32x4 bs[4][2];
; #pragma unroll
;                 for (int m = 0; m < 4; ++m) { const size_t off = (size_t)(row0 + ai * HALF + m * 16) * DM + col0;
; #pragma unroll
;                     for (int bj = 0; bj < 2; ++bj) bs[m][bj] = *(const u32x4*)(baseb + off + bj * HALF); }
; #pragma unroll
;                 for (int m = 0; m < 4; ++m) { const size_t off = (size_t)(row0 + ai * HALF + m * 16) * DM + col0;
;                     float ss = 0.f;
; #pragma unroll
;                     for (int bj = 0; bj < 2; ++bj) { const u32x4 q = bs[m][bj]; const f32x4 a0 = acc[ai][bj][m][0], a1 = acc[ai][bj][m][1];
;                         const float h0 = bflo(q.x) + a0[0], h1 = bfhi(q.x) + a0[1], h2 = bflo(q.y) + a0[2], h3 = bfhi(q.y) + a0[3], h4 = bflo(q.z) + a1[0], h5 = bfhi(q.z) + a1[1], h6 = bflo(q.w) + a1[2], h7 = bfhi(q.w) + a1[3];
;                         ss += (h0 * h0 + h1 * h1) + (h2 * h2 + h3 * h3) + (h4 * h4 + h5 * h5) + (h6 * h6 + h7 * h7);
;                         u32x4 w; w.x = pk2(h0, h1); w.y = pk2(h2, h3); w.z = pk2(h4, h5); w.w = pk2(h6, h7);
;                         *(u32x4*)(out + off + bj * HALF) = w; }
;                     if (ssqp) { ss += __shfl_xor(ss, 16); ss += __shfl_xor(ss, 32); if (fq == 0) ssqp[(size_t)(row0 + ai * HALF + m * 16) * 32 + u.pn * 4 + wc] = ss; } }
	v_lshl_or_b32 v168, s6, 8, v188
	v_lshl_add_u32 v172, s8, 8, v186
	v_ashrrev_i32_e32 v169, 31, v168
	v_lshlrev_b64 v[202:203], 1, v[168:169]
	v_ashrrev_i32_e32 v173, 31, v172
	v_or_b32_e32 v182, 16, v172
	v_or_b32_e32 v178, 32, v172
	v_lshl_add_u64 v[170:171], s[22:23], 0, v[202:203]
	v_lshlrev_b64 v[204:205], 12, v[172:173]
	v_or_b32_e32 v174, 48, v172
	v_ashrrev_i32_e32 v183, 31, v182
	v_ashrrev_i32_e32 v179, 31, v178
	v_lshl_add_u64 v[128:129], v[170:171], 0, v[204:205]
	v_ashrrev_i32_e32 v175, 31, v174
	v_lshlrev_b64 v[184:185], 12, v[182:183]
	v_lshlrev_b64 v[180:181], 12, v[178:179]
	global_load_dwordx4 v[194:197], v[128:129], off
	global_load_dwordx4 v[198:201], v[128:129], off offset:256
	v_lshlrev_b64 v[176:177], 12, v[174:175]
	v_lshl_add_u64 v[128:129], v[170:171], 0, v[184:185]
	v_lshl_add_u64 v[130:131], v[170:171], 0, v[180:181]
	v_lshl_add_u64 v[206:207], v[170:171], 0, v[176:177]
	global_load_dwordx4 v[148:151], v[128:129], off
	global_load_dwordx4 v[144:147], v[128:129], off offset:256
	global_load_dwordx4 v[140:143], v[130:131], off
	global_load_dwordx4 v[136:139], v[130:131], off offset:256
	global_load_dwordx4 v[132:135], v[206:207], off
	s_nop 0
	global_load_dwordx4 v[128:131], v[206:207], off offset:256
	s_mov_b64 s[100:101], 0x80000
	v_lshl_add_u64 v[244:245], v[170:171], 0, s[100:101]
	v_lshl_add_u64 v[246:247], v[244:245], 0, v[204:205]
	global_load_dwordx4 v[212:215], v[246:247], off
	global_load_dwordx4 v[216:219], v[246:247], off offset:256
	v_lshl_add_u64 v[246:247], v[244:245], 0, v[184:185]
	global_load_dwordx4 v[220:223], v[246:247], off
	global_load_dwordx4 v[224:227], v[246:247], off offset:256
	v_lshl_add_u64 v[246:247], v[244:245], 0, v[180:181]
	global_load_dwordx4 v[228:231], v[246:247], off
	global_load_dwordx4 v[232:235], v[246:247], off offset:256
	v_lshl_add_u64 v[246:247], v[244:245], 0, v[176:177]
	global_load_dwordx4 v[236:239], v[246:247], off
	global_load_dwordx4 v[240:243], v[246:247], off offset:256
	v_cndmask_b32_e64 v193, 0, 1, s[10:11]
	v_lshl_add_u64 v[204:205], s[22:23], 0, v[204:205]
	s_lshl_b32 s26, s6, 2
	v_cmp_ne_u32_e64 s[6:7], 1, v193
	v_lshl_add_u64 v[204:205], v[204:205], 0, v[202:203]
	s_ashr_i32 s27, s26, 31
	s_andn2_b64 vcc, exec, s[10:11]
	s_waitcnt vmcnt(0)
	v_lshlrev_b32_e32 v193, 16, v194
	v_and_b32_e32 v194, 0xffff0000, v194
	v_lshlrev_b32_e32 v202, 16, v195
	v_and_b32_e32 v195, 0xffff0000, v195
	v_lshlrev_b32_e32 v203, 16, v196
	v_and_b32_e32 v196, 0xffff0000, v196
	v_lshlrev_b32_e32 v206, 16, v197
	v_and_b32_e32 v197, 0xffff0000, v197
	v_lshlrev_b32_e32 v207, 16, v198
	v_and_b32_e32 v198, 0xffff0000, v198
	v_lshlrev_b32_e32 v208, 16, v199
	v_and_b32_e32 v199, 0xffff0000, v199
	v_lshlrev_b32_e32 v209, 16, v200
	v_and_b32_e32 v200, 0xffff0000, v200
	v_lshlrev_b32_e32 v210, 16, v201
	v_and_b32_e32 v201, 0xffff0000, v201
	v_add_f32_e32 v193, v124, v193
	v_add_f32_e32 v194, v125, v194
	v_add_f32_e32 v124, v126, v202
	v_add_f32_e32 v125, v127, v195
	v_add_f32_e32 v126, v120, v203
	v_add_f32_e32 v127, v121, v196
	v_add_f32_e32 v122, v122, v206
	v_add_f32_e32 v123, v123, v197
	v_add_f32_e32 v120, v116, v207
	v_add_f32_e32 v121, v117, v198
	v_add_f32_e32 v116, v118, v208
	v_add_f32_e32 v117, v119, v199
	v_add_f32_e32 v112, v112, v209
	v_add_f32_e32 v113, v113, v200
	v_add_f32_e32 v114, v114, v210
	v_add_f32_e32 v115, v115, v201
	v_cvt_pk_bf16_f32 v196, v193, v194
	v_cvt_pk_bf16_f32 v197, v124, v125
	v_cvt_pk_bf16_f32 v198, v126, v127
	v_cvt_pk_bf16_f32 v199, v122, v123
	v_cvt_pk_bf16_f32 v200, v120, v121
	v_cvt_pk_bf16_f32 v201, v116, v117
	v_cvt_pk_bf16_f32 v202, v112, v113
	v_cvt_pk_bf16_f32 v203, v114, v115
	global_store_dwordx4 v[204:205], v[196:199], off
	global_store_dwordx4 v[204:205], v[200:203], off offset:256
	s_cbranch_vccnz .LBB0_851
	v_mul_f32_e32 v115, v115, v115
	v_mul_f32_e32 v113, v113, v113
	v_mul_f32_e32 v118, v123, v123
	v_fmac_f32_e32 v115, v114, v114
	v_fmac_f32_e32 v113, v112, v112
	v_mul_f32_e32 v112, v121, v121
	v_mul_f32_e32 v114, v117, v117
	v_fmac_f32_e32 v118, v122, v122
	v_mul_f32_e32 v122, v194, v194
	v_mul_f32_e32 v123, v125, v125
	v_fmac_f32_e32 v112, v120, v120
	v_fmac_f32_e32 v114, v116, v116
	v_mul_f32_e32 v119, v127, v127
	v_fmac_f32_e32 v122, v193, v193
	v_fmac_f32_e32 v123, v124, v124
	v_add_f32_e32 v112, v112, v114
	v_and_b32_e32 v114, 64, v192
	v_fmac_f32_e32 v119, v126, v126
	v_add_f32_e32 v122, v122, v123
	v_add_f32_e32 v112, v113, v112
	v_xor_b32_e32 v113, 16, v192
	v_add_u32_e32 v114, 64, v114
	v_add_f32_e32 v119, v119, v122
	v_cmp_lt_i32_e32 vcc, v113, v114
	v_add_f32_e32 v118, v118, v119
	v_add_f32_e32 v112, v115, v112
	v_cndmask_b32_e32 v113, v192, v113, vcc
	v_add_f32_e32 v112, v118, v112
	v_lshlrev_b32_e32 v113, 2, v113
	ds_bpermute_b32 v113, v113, v112
	s_waitcnt lgkmcnt(0)
	v_add_f32_e32 v112, v112, v113
	v_xor_b32_e32 v113, 32, v192
	v_cmp_lt_i32_e32 vcc, v113, v114
	s_nop 1
	v_cndmask_b32_e32 v113, v192, v113, vcc
	v_lshlrev_b32_e32 v113, 2, v113
	ds_bpermute_b32 v113, v113, v112
	s_and_saveexec_b64 s[28:29], s[0:1]
	s_cbranch_execz .LBB0_850
	v_lshlrev_b64 v[114:115], 7, v[172:173]
	v_lshl_add_u64 v[114:115], s[24:25], 0, v[114:115]
	v_lshl_add_u64 v[114:115], s[26:27], 2, v[114:115]
	s_lshl_b32 s8, s40, 2
	v_lshl_add_u64 v[114:115], v[114:115], 0, s[8:9]
	s_waitcnt lgkmcnt(0)
	v_add_f32_e32 v112, v112, v113
	global_store_dword v[114:115], v112, off

; __device__ __forceinline__ float bflo(unsigned w) { return __uint_as_float(w << 16); }
; __device__ __forceinline__ float bfhi(unsigned w) { return __uint_as_float(w & 0xffff0000u); }
;     __device__ __forceinline__ void operator()(const f32x4 (&acc)[2][2][4][2], const Unit& u, int wr, int wc, int fr, int fq) const {
;     ...
;                 for (int m = 0; m < 4; ++m) { const size_t off = (size_t)(row0 + ai * HALF + m * 16) * DM + col0;
;                     float ss = 0.f;
; #pragma unroll
;                     for (int bj = 0; bj < 2; ++bj) { const u32x4 q = bs[m][bj]; const f32x4 a0 = acc[ai][bj][m][0], a1 = acc[ai][bj][m][1];
;                         const float h0 = bflo(q.x) + a0[0], h1 = bfhi(q.x) + a0[1], h2 = bflo(q.y) + a0[2], h3 = bfhi(q.y) + a0[3], h4 = bflo(q.z) + a1[0], h5 = bfhi(q.z) + a1[1], h6 = bflo(q.w) + a1[2], h7 = bfhi(q.w) + a1[3];
;                         ss += (h0 * h0 + h1 * h1) + (h2 * h2 + h3 * h3) + (h4 * h4 + h5 * h5) + (h6 * h6 + h7 * h7);
;                         u32x4 w; w.x = pk2(h0, h1); w.y = pk2(h2, h3); w.z = pk2(h4, h5); w.w = pk2(h6, h7);
;                         *(u32x4*)(out + off + bj * HALF) = w; }
;                     if (ssqp) { ss += __shfl_xor(ss, 16); ss += __shfl_xor(ss, 32); if (fq == 0) ssqp[(size_t)(row0 + ai * HALF + m * 16) * 32 + u.pn * 4 + wc] = ss; } }
.LBB0_863:
	v_add_u32_e32 v100, 0x80, v172
	v_ashrrev_i32_e32 v101, 31, v100
	v_add_u32_e32 v96, 0x90, v172
	v_add_u32_e32 v92, 0xa0, v172
	v_lshlrev_b64 v[110:111], 12, v[100:101]
	v_add_u32_e32 v88, 0xb0, v172
	s_waitcnt lgkmcnt(0)
	v_ashrrev_i32_e32 v97, 31, v96
	v_ashrrev_i32_e32 v93, 31, v92
	v_lshl_add_u64 v[64:65], v[170:171], 0, v[110:111]
	v_ashrrev_i32_e32 v89, 31, v88
	v_lshlrev_b64 v[98:99], 12, v[96:97]
	v_lshlrev_b64 v[94:95], 12, v[92:93]
	v_mov_b32_e32 v102, v212
	v_mov_b32_e32 v103, v213
	v_mov_b32_e32 v104, v214
	v_mov_b32_e32 v105, v215
	v_mov_b32_e32 v106, v216
	v_mov_b32_e32 v107, v217
	v_mov_b32_e32 v108, v218
	v_mov_b32_e32 v109, v219
	v_lshlrev_b64 v[90:91], 12, v[88:89]
	v_lshl_add_u64 v[64:65], v[170:171], 0, v[98:99]
	v_lshl_add_u64 v[66:67], v[170:171], 0, v[94:95]
	v_lshl_add_u64 v[112:113], v[170:171], 0, v[90:91]
	v_mov_b32_e32 v84, v220
	v_mov_b32_e32 v85, v221
	v_mov_b32_e32 v86, v222
	v_mov_b32_e32 v87, v223
	v_mov_b32_e32 v80, v224
	v_mov_b32_e32 v81, v225
	v_mov_b32_e32 v82, v226
	v_mov_b32_e32 v83, v227
	v_mov_b32_e32 v76, v228
	v_mov_b32_e32 v77, v229
	v_mov_b32_e32 v78, v230
	v_mov_b32_e32 v79, v231
	v_mov_b32_e32 v72, v232
	v_mov_b32_e32 v73, v233
	v_mov_b32_e32 v74, v234
	v_mov_b32_e32 v75, v235
	v_mov_b32_e32 v68, v236
	v_mov_b32_e32 v69, v237
	v_mov_b32_e32 v70, v238
	v_mov_b32_e32 v71, v239
	v_mov_b32_e32 v64, v240
	v_mov_b32_e32 v65, v241
	v_mov_b32_e32 v66, v242
	v_mov_b32_e32 v67, v243
	v_lshl_add_u64 v[110:111], s[22:23], 0, v[110:111]
	v_lshl_add_u64 v[112:113], v[168:169], 1, v[110:111]
	s_and_b64 vcc, exec, s[6:7]
	v_lshlrev_b32_e32 v110, 16, v102
	v_and_b32_e32 v111, 0xffff0000, v102
	v_lshlrev_b32_e32 v114, 16, v103
	v_and_b32_e32 v115, 0xffff0000, v103
	v_lshlrev_b32_e32 v116, 16, v104
	v_and_b32_e32 v104, 0xffff0000, v104
	v_lshlrev_b32_e32 v117, 16, v105
	v_and_b32_e32 v105, 0xffff0000, v105
	v_lshlrev_b32_e32 v118, 16, v106
	v_and_b32_e32 v106, 0xffff0000, v106
	v_lshlrev_b32_e32 v119, 16, v107
	v_and_b32_e32 v107, 0xffff0000, v107
	v_lshlrev_b32_e32 v120, 16, v108
	v_and_b32_e32 v108, 0xffff0000, v108
	v_lshlrev_b32_e32 v121, 16, v109
	v_and_b32_e32 v109, 0xffff0000, v109
	v_add_f32_e32 v102, v60, v110
	v_add_f32_e32 v103, v61, v111
	v_add_f32_e32 v60, v62, v114
	v_add_f32_e32 v61, v63, v115
	v_add_f32_e32 v62, v56, v116
	v_add_f32_e32 v63, v57, v104
	v_add_f32_e32 v58, v58, v117
	v_add_f32_e32 v59, v59, v105
	v_add_f32_e32 v56, v52, v118
	v_add_f32_e32 v57, v53, v106
	v_add_f32_e32 v52, v54, v119
	v_add_f32_e32 v53, v55, v107
	v_add_f32_e32 v48, v48, v120
	v_add_f32_e32 v49, v49, v108
	v_add_f32_e32 v50, v50, v121
	v_add_f32_e32 v51, v51, v109
	v_cvt_pk_bf16_f32 v104, v102, v103
	v_cvt_pk_bf16_f32 v105, v60, v61
	v_cvt_pk_bf16_f32 v106, v62, v63
	v_cvt_pk_bf16_f32 v107, v58, v59
	v_cvt_pk_bf16_f32 v108, v56, v57
	v_cvt_pk_bf16_f32 v109, v52, v53
	v_cvt_pk_bf16_f32 v110, v48, v49
	v_cvt_pk_bf16_f32 v111, v50, v51
	global_store_dwordx4 v[112:113], v[104:107], off
	global_store_dwordx4 v[112:113], v[108:111], off offset:256
	s_cbranch_vccnz .LBB0_867
	v_mul_f32_e32 v51, v51, v51
	v_mul_f32_e32 v49, v49, v49
	v_mul_f32_e32 v54, v59, v59
	v_fmac_f32_e32 v51, v50, v50
	v_fmac_f32_e32 v49, v48, v48
	v_mul_f32_e32 v48, v57, v57
	v_mul_f32_e32 v50, v53, v53
	v_fmac_f32_e32 v54, v58, v58
	v_mul_f32_e32 v58, v103, v103
	v_mul_f32_e32 v59, v61, v61
	v_fmac_f32_e32 v48, v56, v56
	v_fmac_f32_e32 v50, v52, v52
	v_mul_f32_e32 v55, v63, v63
	v_fmac_f32_e32 v58, v102, v102
	v_fmac_f32_e32 v59, v60, v60
	v_add_f32_e32 v48, v48, v50
	v_and_b32_e32 v50, 64, v192
	v_fmac_f32_e32 v55, v62, v62
	v_add_f32_e32 v58, v58, v59
	v_add_f32_e32 v48, v49, v48
	v_xor_b32_e32 v49, 16, v192
	v_add_u32_e32 v50, 64, v50
	v_add_f32_e32 v55, v55, v58
	v_cmp_lt_i32_e32 vcc, v49, v50
	v_add_f32_e32 v54, v54, v55
	v_add_f32_e32 v48, v51, v48
	v_cndmask_b32_e32 v49, v192, v49, vcc
	v_add_f32_e32 v48, v54, v48
	v_lshlrev_b32_e32 v49, 2, v49
	ds_bpermute_b32 v49, v49, v48
	s_waitcnt lgkmcnt(0)
	v_add_f32_e32 v48, v48, v49
	v_xor_b32_e32 v49, 32, v192
	v_cmp_lt_i32_e32 vcc, v49, v50
	s_nop 1
	v_cndmask_b32_e32 v49, v192, v49, vcc
	v_lshlrev_b32_e32 v49, 2, v49
	ds_bpermute_b32 v49, v49, v48
	s_and_saveexec_b64 s[28:29], s[0:1]
	s_cbranch_execz .LBB0_866
	v_lshlrev_b64 v[50:51], 7, v[100:101]
	v_lshl_add_u64 v[50:51], s[24:25], 0, v[50:51]
	v_lshl_add_u64 v[50:51], s[26:27], 2, v[50:51]
	s_lshl_b32 s8, s40, 2
	v_lshl_add_u64 v[50:51], v[50:51], 0, s[8:9]
	s_waitcnt lgkmcnt(0)
	v_add_f32_e32 v48, v48, v49
	global_store_dword v[50:51], v48, off

; __device__ __forceinline__ float bflo(unsigned w) { return __uint_as_float(w << 16); }
; __device__ __forceinline__ float bfhi(unsigned w) { return __uint_as_float(w & 0xffff0000u); }
;     __device__ __forceinline__ void operator()(const f32x4 (&acc)[2][2][4][2], const Unit& u, int wr, int wc, int fr, int fq) const {
;     ...
;                 for (int m = 0; m < 4; ++m) { const size_t off = (size_t)(row0 + ai * HALF + m * 16) * DM + col0;
;                     float ss = 0.f;
; #pragma unroll
;                     for (int bj = 0; bj < 2; ++bj) { const u32x4 q = bs[m][bj]; const f32x4 a0 = acc[ai][bj][m][0], a1 = acc[ai][bj][m][1];
;                         const float h0 = bflo(q.x) + a0[0], h1 = bfhi(q.x) + a0[1], h2 = bflo(q.y) + a0[2], h3 = bfhi(q.y) + a0[3], h4 = bflo(q.z) + a1[0], h5 = bfhi(q.z) + a1[1], h6 = bflo(q.w) + a1[2], h7 = bfhi(q.w) + a1[3];
;                         ss += (h0 * h0 + h1 * h1) + (h2 * h2 + h3 * h3) + (h4 * h4 + h5 * h5) + (h6 * h6 + h7 * h7);
;                         u32x4 w; w.x = pk2(h0, h1); w.y = pk2(h2, h3); w.z = pk2(h4, h5); w.w = pk2(h6, h7);
;                         *(u32x4*)(out + off + bj * HALF) = w; }
;                     if (ssqp) { ss += __shfl_xor(ss, 16); ss += __shfl_xor(ss, 32); if (fq == 0) ssqp[(size_t)(row0 + ai * HALF + m * 16) * 32 + u.pn * 4 + wc] = ss; } }
.LBB0_867:
	v_lshlrev_b32_e32 v48, 16, v84
	v_add_f32_e32 v44, v44, v48
	v_and_b32_e32 v48, 0xffff0000, v84
	v_add_f32_e32 v48, v45, v48
	v_lshlrev_b32_e32 v45, 16, v85
	v_add_f32_e32 v45, v46, v45
	v_and_b32_e32 v46, 0xffff0000, v85
	v_add_f32_e32 v46, v47, v46
	v_lshlrev_b32_e32 v47, 16, v86
	v_add_f32_e32 v40, v40, v47
	v_and_b32_e32 v47, 0xffff0000, v86
	v_add_f32_e32 v41, v41, v47
	v_lshlrev_b32_e32 v47, 16, v87
	v_add_f32_e32 v47, v42, v47
	v_and_b32_e32 v42, 0xffff0000, v87
	v_add_f32_e32 v43, v43, v42
	v_lshlrev_b32_e32 v42, 16, v80
	v_add_f32_e32 v36, v36, v42
	v_and_b32_e32 v42, 0xffff0000, v80
	v_add_f32_e32 v42, v37, v42
	v_lshlrev_b32_e32 v37, 16, v81
	v_add_f32_e32 v37, v38, v37
	v_and_b32_e32 v38, 0xffff0000, v81
	v_add_f32_e32 v38, v39, v38
	v_lshlrev_b32_e32 v39, 16, v82
	v_add_f32_e32 v32, v32, v39
	v_and_b32_e32 v39, 0xffff0000, v82
	v_add_f32_e32 v33, v33, v39
	v_lshlrev_b32_e32 v39, 16, v83
	v_lshl_add_u64 v[54:55], s[22:23], 0, v[98:99]
	v_add_f32_e32 v34, v34, v39
	v_and_b32_e32 v39, 0xffff0000, v83
	v_cvt_pk_bf16_f32 v50, v44, v48
	v_cvt_pk_bf16_f32 v51, v45, v46
	v_cvt_pk_bf16_f32 v52, v40, v41
	v_cvt_pk_bf16_f32 v53, v47, v43
	v_lshl_add_u64 v[54:55], v[168:169], 1, v[54:55]
	v_add_f32_e32 v35, v35, v39
	global_store_dwordx4 v[54:55], v[50:53], off
	s_and_b64 vcc, exec, s[6:7]
	s_nop 0
	v_cvt_pk_bf16_f32 v50, v36, v42
	v_cvt_pk_bf16_f32 v51, v37, v38
	v_cvt_pk_bf16_f32 v52, v32, v33
	v_cvt_pk_bf16_f32 v53, v34, v35
	global_store_dwordx4 v[54:55], v[50:53], off offset:256
	s_cbranch_vccnz .LBB0_871
	v_mul_f32_e32 v35, v35, v35
	v_mul_f32_e32 v33, v33, v33
	v_mul_f32_e32 v41, v41, v41
	v_fmac_f32_e32 v35, v34, v34
	v_fmac_f32_e32 v33, v32, v32
	v_mul_f32_e32 v32, v42, v42
	v_mul_f32_e32 v34, v38, v38
	v_mul_f32_e32 v39, v43, v43
	v_fmac_f32_e32 v41, v40, v40
	v_mul_f32_e32 v40, v48, v48
	v_mul_f32_e32 v43, v46, v46
	v_fmac_f32_e32 v32, v36, v36
	v_fmac_f32_e32 v34, v37, v37
	v_fmac_f32_e32 v40, v44, v44
	v_fmac_f32_e32 v43, v45, v45
	v_add_f32_e32 v32, v32, v34
	v_and_b32_e32 v34, 64, v192
	v_add_f32_e32 v40, v40, v43
	v_add_f32_e32 v32, v33, v32
	v_xor_b32_e32 v33, 16, v192
	v_add_u32_e32 v34, 64, v34
	v_fmac_f32_e32 v39, v47, v47
	v_add_f32_e32 v40, v41, v40
	v_cmp_lt_i32_e32 vcc, v33, v34
	v_add_f32_e32 v39, v39, v40
	v_add_f32_e32 v32, v35, v32
	v_cndmask_b32_e32 v33, v192, v33, vcc
	v_add_f32_e32 v32, v39, v32
	v_lshlrev_b32_e32 v33, 2, v33
	ds_bpermute_b32 v33, v33, v32
	s_waitcnt lgkmcnt(0)
	v_add_f32_e32 v32, v32, v33
	v_xor_b32_e32 v33, 32, v192
	v_cmp_lt_i32_e32 vcc, v33, v34
	s_nop 1
	v_cndmask_b32_e32 v33, v192, v33, vcc
	v_lshlrev_b32_e32 v33, 2, v33
	ds_bpermute_b32 v33, v33, v32
	s_and_saveexec_b64 s[28:29], s[0:1]
	s_cbranch_execz .LBB0_870
	v_lshlrev_b64 v[34:35], 7, v[96:97]
	v_lshl_add_u64 v[34:35], s[24:25], 0, v[34:35]
	v_lshl_add_u64 v[34:35], s[26:27], 2, v[34:35]
	s_lshl_b32 s8, s40, 2
	v_lshl_add_u64 v[34:35], v[34:35], 0, s[8:9]
	s_waitcnt lgkmcnt(0)
	v_add_f32_e32 v32, v32, v33
	global_store_dword v[34:35], v32, off

; __device__ __forceinline__ float bflo(unsigned w) { return __uint_as_float(w << 16); }
; __device__ __forceinline__ float bfhi(unsigned w) { return __uint_as_float(w & 0xffff0000u); }
;     __device__ __forceinline__ void operator()(const f32x4 (&acc)[2][2][4][2], const Unit& u, int wr, int wc, int fr, int fq) const {
;     ...
;                 for (int m = 0; m < 4; ++m) { const size_t off = (size_t)(row0 + ai * HALF + m * 16) * DM + col0;
;                     float ss = 0.f;
; #pragma unroll
;                     for (int bj = 0; bj < 2; ++bj) { const u32x4 q = bs[m][bj]; const f32x4 a0 = acc[ai][bj][m][0], a1 = acc[ai][bj][m][1];
;                         const float h0 = bflo(q.x) + a0[0], h1 = bfhi(q.x) + a0[1], h2 = bflo(q.y) + a0[2], h3 = bfhi(q.y) + a0[3], h4 = bflo(q.z) + a1[0], h5 = bfhi(q.z) + a1[1], h6 = bflo(q.w) + a1[2], h7 = bfhi(q.w) + a1[3];
;                         ss += (h0 * h0 + h1 * h1) + (h2 * h2 + h3 * h3) + (h4 * h4 + h5 * h5) + (h6 * h6 + h7 * h7);
;                         u32x4 w; w.x = pk2(h0, h1); w.y = pk2(h2, h3); w.z = pk2(h4, h5); w.w = pk2(h6, h7);
;                         *(u32x4*)(out + off + bj * HALF) = w; }
;                     if (ssqp) { ss += __shfl_xor(ss, 16); ss += __shfl_xor(ss, 32); if (fq == 0) ssqp[(size_t)(row0 + ai * HALF + m * 16) * 32 + u.pn * 4 + wc] = ss; } }
.LBB0_871:
	v_lshlrev_b32_e32 v32, 16, v76
	v_add_f32_e32 v28, v28, v32
	v_and_b32_e32 v32, 0xffff0000, v76
	v_add_f32_e32 v32, v29, v32
	v_lshlrev_b32_e32 v29, 16, v77
	v_add_f32_e32 v29, v30, v29
	v_and_b32_e32 v30, 0xffff0000, v77
	v_add_f32_e32 v30, v31, v30
	v_lshlrev_b32_e32 v31, 16, v78
	v_add_f32_e32 v24, v24, v31
	v_and_b32_e32 v31, 0xffff0000, v78
	v_add_f32_e32 v25, v25, v31
	v_lshlrev_b32_e32 v31, 16, v79
	v_add_f32_e32 v31, v26, v31
	v_and_b32_e32 v26, 0xffff0000, v79
	v_add_f32_e32 v27, v27, v26
	v_lshlrev_b32_e32 v26, 16, v72
	v_add_f32_e32 v20, v20, v26
	v_and_b32_e32 v26, 0xffff0000, v72
	v_add_f32_e32 v26, v21, v26
	v_lshlrev_b32_e32 v21, 16, v73
	v_add_f32_e32 v21, v22, v21
	v_and_b32_e32 v22, 0xffff0000, v73
	v_add_f32_e32 v22, v23, v22
	v_lshlrev_b32_e32 v23, 16, v74
	v_add_f32_e32 v16, v16, v23
	v_and_b32_e32 v23, 0xffff0000, v74
	v_add_f32_e32 v17, v17, v23
	v_lshlrev_b32_e32 v23, 16, v75
	v_lshl_add_u64 v[38:39], s[22:23], 0, v[94:95]
	v_add_f32_e32 v18, v18, v23
	v_and_b32_e32 v23, 0xffff0000, v75
	v_cvt_pk_bf16_f32 v34, v28, v32
	v_cvt_pk_bf16_f32 v35, v29, v30
	v_cvt_pk_bf16_f32 v36, v24, v25
	v_cvt_pk_bf16_f32 v37, v31, v27
	v_lshl_add_u64 v[38:39], v[168:169], 1, v[38:39]
	v_add_f32_e32 v19, v19, v23
	global_store_dwordx4 v[38:39], v[34:37], off
	s_and_b64 vcc, exec, s[6:7]
	s_nop 0
	v_cvt_pk_bf16_f32 v34, v20, v26
	v_cvt_pk_bf16_f32 v35, v21, v22
	v_cvt_pk_bf16_f32 v36, v16, v17
	v_cvt_pk_bf16_f32 v37, v18, v19
	global_store_dwordx4 v[38:39], v[34:37], off offset:256
	s_cbranch_vccnz .LBB0_875
	v_mul_f32_e32 v19, v19, v19
	v_mul_f32_e32 v17, v17, v17
	v_mul_f32_e32 v25, v25, v25
	v_fmac_f32_e32 v19, v18, v18
	v_fmac_f32_e32 v17, v16, v16
	v_mul_f32_e32 v16, v26, v26
	v_mul_f32_e32 v18, v22, v22
	v_mul_f32_e32 v23, v27, v27
	v_fmac_f32_e32 v25, v24, v24
	v_mul_f32_e32 v24, v32, v32
	v_mul_f32_e32 v27, v30, v30
	v_fmac_f32_e32 v16, v20, v20
	v_fmac_f32_e32 v18, v21, v21
	v_fmac_f32_e32 v24, v28, v28
	v_fmac_f32_e32 v27, v29, v29
	v_add_f32_e32 v16, v16, v18
	v_and_b32_e32 v18, 64, v192
	v_add_f32_e32 v24, v24, v27
	v_add_f32_e32 v16, v17, v16
	v_xor_b32_e32 v17, 16, v192
	v_add_u32_e32 v18, 64, v18
	v_fmac_f32_e32 v23, v31, v31
	v_add_f32_e32 v24, v25, v24
	v_cmp_lt_i32_e32 vcc, v17, v18
	v_add_f32_e32 v23, v23, v24
	v_add_f32_e32 v16, v19, v16
	v_cndmask_b32_e32 v17, v192, v17, vcc
	v_add_f32_e32 v16, v23, v16
	v_lshlrev_b32_e32 v17, 2, v17
	ds_bpermute_b32 v17, v17, v16
	s_waitcnt lgkmcnt(0)
	v_add_f32_e32 v16, v16, v17
	v_xor_b32_e32 v17, 32, v192
	v_cmp_lt_i32_e32 vcc, v17, v18
	s_nop 1
	v_cndmask_b32_e32 v17, v192, v17, vcc
	v_lshlrev_b32_e32 v17, 2, v17
	ds_bpermute_b32 v17, v17, v16
	s_and_saveexec_b64 s[28:29], s[0:1]
	s_cbranch_execz .LBB0_874
	v_lshlrev_b64 v[18:19], 7, v[92:93]
	v_lshl_add_u64 v[18:19], s[24:25], 0, v[18:19]
	v_lshl_add_u64 v[18:19], s[26:27], 2, v[18:19]
	s_lshl_b32 s8, s40, 2
	v_lshl_add_u64 v[18:19], v[18:19], 0, s[8:9]
	s_waitcnt lgkmcnt(0)
	v_add_f32_e32 v16, v16, v17
	global_store_dword v[18:19], v16, off

; __device__ __forceinline__ float bflo(unsigned w) { return __uint_as_float(w << 16); }
; __device__ __forceinline__ float bfhi(unsigned w) { return __uint_as_float(w & 0xffff0000u); }
;     __device__ __forceinline__ void operator()(const f32x4 (&acc)[2][2][4][2], const Unit& u, int wr, int wc, int fr, int fq) const {
;     ...
;                 for (int m = 0; m < 4; ++m) { const size_t off = (size_t)(row0 + ai * HALF + m * 16) * DM + col0;
;                     float ss = 0.f;
; #pragma unroll
;                     for (int bj = 0; bj < 2; ++bj) { const u32x4 q = bs[m][bj]; const f32x4 a0 = acc[ai][bj][m][0], a1 = acc[ai][bj][m][1];
;                         const float h0 = bflo(q.x) + a0[0], h1 = bfhi(q.x) + a0[1], h2 = bflo(q.y) + a0[2], h3 = bfhi(q.y) + a0[3], h4 = bflo(q.z) + a1[0], h5 = bfhi(q.z) + a1[1], h6 = bflo(q.w) + a1[2], h7 = bfhi(q.w) + a1[3];
;                         ss += (h0 * h0 + h1 * h1) + (h2 * h2 + h3 * h3) + (h4 * h4 + h5 * h5) + (h6 * h6 + h7 * h7);
;                         u32x4 w; w.x = pk2(h0, h1); w.y = pk2(h2, h3); w.z = pk2(h4, h5); w.w = pk2(h6, h7);
;                         *(u32x4*)(out + off + bj * HALF) = w; }
;                     if (ssqp) { ss += __shfl_xor(ss, 16); ss += __shfl_xor(ss, 32); if (fq == 0) ssqp[(size_t)(row0 + ai * HALF + m * 16) * 32 + u.pn * 4 + wc] = ss; } }
.LBB0_875:
	v_lshlrev_b32_e32 v16, 16, v68
	v_add_f32_e32 v12, v12, v16
	v_and_b32_e32 v16, 0xffff0000, v68
	v_add_f32_e32 v16, v13, v16
	v_lshlrev_b32_e32 v13, 16, v69
	v_add_f32_e32 v13, v14, v13
	v_and_b32_e32 v14, 0xffff0000, v69
	v_add_f32_e32 v14, v15, v14
	v_lshlrev_b32_e32 v15, 16, v70
	v_add_f32_e32 v8, v8, v15
	v_and_b32_e32 v15, 0xffff0000, v70
	v_add_f32_e32 v9, v9, v15
	v_lshlrev_b32_e32 v15, 16, v71
	v_add_f32_e32 v15, v10, v15
	v_and_b32_e32 v10, 0xffff0000, v71
	v_add_f32_e32 v11, v11, v10
	v_lshlrev_b32_e32 v10, 16, v64
	v_add_f32_e32 v4, v4, v10
	v_and_b32_e32 v10, 0xffff0000, v64
	v_add_f32_e32 v10, v5, v10
	v_lshlrev_b32_e32 v5, 16, v65
	v_add_f32_e32 v5, v6, v5
	v_and_b32_e32 v6, 0xffff0000, v65
	v_add_f32_e32 v6, v7, v6
	v_lshlrev_b32_e32 v7, 16, v66
	v_add_f32_e32 v0, v0, v7
	v_and_b32_e32 v7, 0xffff0000, v66
	v_add_f32_e32 v1, v1, v7
	v_lshlrev_b32_e32 v7, 16, v67
	v_lshl_add_u64 v[22:23], s[22:23], 0, v[90:91]
	v_add_f32_e32 v2, v2, v7
	v_and_b32_e32 v7, 0xffff0000, v67
	v_cvt_pk_bf16_f32 v18, v12, v16
	v_cvt_pk_bf16_f32 v19, v13, v14
	v_cvt_pk_bf16_f32 v20, v8, v9
	v_cvt_pk_bf16_f32 v21, v15, v11
	v_lshl_add_u64 v[22:23], v[168:169], 1, v[22:23]
	v_add_f32_e32 v3, v3, v7
	global_store_dwordx4 v[22:23], v[18:21], off
	s_and_b64 vcc, exec, s[6:7]
	s_nop 0
	v_cvt_pk_bf16_f32 v18, v4, v10
	v_cvt_pk_bf16_f32 v19, v5, v6
	v_cvt_pk_bf16_f32 v20, v0, v1
	v_cvt_pk_bf16_f32 v21, v2, v3
	global_store_dwordx4 v[22:23], v[18:21], off offset:256
	s_cbranch_vccnz .LBB0_838
	v_mul_f32_e32 v3, v3, v3
	v_mul_f32_e32 v1, v1, v1
	v_mul_f32_e32 v9, v9, v9
	v_fmac_f32_e32 v3, v2, v2
	v_fmac_f32_e32 v1, v0, v0
	v_mul_f32_e32 v0, v10, v10
	v_mul_f32_e32 v2, v6, v6
	v_mul_f32_e32 v7, v11, v11
	v_fmac_f32_e32 v9, v8, v8
	v_mul_f32_e32 v8, v16, v16
	v_mul_f32_e32 v11, v14, v14
	v_fmac_f32_e32 v0, v4, v4
	v_fmac_f32_e32 v2, v5, v5
	v_fmac_f32_e32 v8, v12, v12
	v_fmac_f32_e32 v11, v13, v13
	v_add_f32_e32 v0, v0, v2
	v_and_b32_e32 v2, 64, v192
	v_add_f32_e32 v8, v8, v11
	v_add_f32_e32 v0, v1, v0
	v_xor_b32_e32 v1, 16, v192
	v_add_u32_e32 v2, 64, v2
	v_fmac_f32_e32 v7, v15, v15
	v_add_f32_e32 v8, v9, v8
	v_cmp_lt_i32_e32 vcc, v1, v2
	v_add_f32_e32 v7, v7, v8
	v_add_f32_e32 v0, v3, v0
	v_cndmask_b32_e32 v1, v192, v1, vcc
	v_add_f32_e32 v0, v7, v0
	v_lshlrev_b32_e32 v1, 2, v1
	ds_bpermute_b32 v1, v1, v0
	s_waitcnt lgkmcnt(0)
	v_add_f32_e32 v0, v0, v1
	v_xor_b32_e32 v1, 32, v192
	v_cmp_lt_i32_e32 vcc, v1, v2
	s_nop 1
	v_cndmask_b32_e32 v1, v192, v1, vcc
	v_lshlrev_b32_e32 v1, 2, v1
	ds_bpermute_b32 v1, v1, v0
	s_and_saveexec_b64 s[6:7], s[0:1]
	s_cbranch_execz .LBB0_837
	v_lshlrev_b64 v[2:3], 7, v[88:89]
	v_lshl_add_u64 v[2:3], s[24:25], 0, v[2:3]
	v_lshl_add_u64 v[2:3], s[26:27], 2, v[2:3]
	s_lshl_b32 s8, s40, 2
	v_lshl_add_u64 v[2:3], v[2:3], 0, s[8:9]
	s_waitcnt lgkmcnt(0)
	v_add_f32_e32 v0, v0, v1
	global_store_dword v[2:3], v0, off
	s_branch .LBB0_837
